# attention loop issue-slot trimming: PK4 permlane swaps removed via V LDS key-order change, deeper K-fragment prefetch, saddr global loads, fewer LDS base regs
# speedup vs baseline: 1.0147x; 1.0147x over previous
; __device__ __forceinline__ int lane_id_asm() { int l; asm volatile("v_mbcnt_lo_u32_b32 %0, -1, 0\n\tv_mbcnt_hi_u32_b32 %0, -1, %0" : "=v"(l)); return l; }
; __device__ __forceinline__ unsigned xb_ld(unsigned* p)              { return __hip_atomic_load(p, __ATOMIC_RELAXED, __HIP_MEMORY_SCOPE_AGENT); }
; __device__ __forceinline__ unsigned xb_add(unsigned* p, unsigned v) { return __hip_atomic_fetch_add(p, v, __ATOMIC_RELAXED, __HIP_MEMORY_SCOPE_AGENT); }
; __device__ __forceinline__ void grid_bar(unsigned* bar, unsigned x, volatile LAS unsigned* st, unsigned G, int wave) {
;     asm volatile("s_waitcnt vmcnt(0) lgkmcnt(0)" ::: "memory");
;     __syncthreads();
;     if (wave == 0) {
;         if (lane_id_asm() == 0) {
;             unsigned nloc = st[0], nx = st[1];
;             if (nloc == 0u) {
;                 for (;;) { unsigned sum = 0u, cnt = 0u, mine = 0u;
; #pragma unroll
;                     for (unsigned jj = 0; jj < 16; ++jj) { const unsigned c = xb_ld(&bar[XB_XCNT(jj)]); sum += c; cnt += (c > 0u) ? 1u : 0u; mine = (jj == x) ? c : mine; }
;                     if (sum == G) { nloc = mine; nx = cnt; break; }
;                     __builtin_amdgcn_s_sleep(1); }
;                 st[0] = nloc; st[1] = nx;
;             }
;             const unsigned old = xb_add(&bar[XB_XSUB(x)], 1u), gen = old / nloc;
.LBB0_564:
	v_readlane_b32 s48, v254, 6
	v_writelane_b32 v253, s52, 0
	v_writelane_b32 v253, s53, 1
	s_waitcnt lgkmcnt(0)
	s_barrier
	s_cmpk_gt_i32 s48, 0x9ff
	s_cbranch_scc0 .LBB0_570
.LBB0_565:
	s_waitcnt vmcnt(0) lgkmcnt(0)
	v_readlane_b32 s52, v253, 0
	v_readlane_b32 s53, v253, 1
	s_and_b64 vcc, exec, s[36:37]
	s_barrier
	s_cbranch_vccnz .LBB0_620
	v_mbcnt_lo_u32_b32 v0, -1, 0
	v_mbcnt_hi_u32_b32 v0, -1, v0
	s_nop 0
	v_cmp_eq_u32_e32 vcc, 0, v0
	s_and_saveexec_b64 s[82:83], vcc
	s_cbranch_execz .LBB0_619
	v_readlane_b32 s2, v255, 55
	s_nop 1
	v_mov_b32_e32 v0, s2
	ds_read_b32 v1, v0
	v_readlane_b32 s2, v255, 56
	s_waitcnt lgkmcnt(0)
	v_cmp_ne_u32_e32 vcc, 0, v1
	v_mov_b32_e32 v0, s2
	ds_read_b32 v0, v0
	s_cbranch_vccnz .LBB0_597
	v_mov_b32_e32 v1, 0
	s_branch .LBB0_594

; __device__ __forceinline__ int lane_id_asm() { int l; asm volatile("v_mbcnt_lo_u32_b32 %0, -1, 0\n\tv_mbcnt_hi_u32_b32 %0, -1, %0" : "=v"(l)); return l; }
; __device__ __forceinline__ int v_st(int k, int c) { const int kk = (k & ~0xC) | ((k & 4) << 1) | ((k & 8) >> 1); return ((kk >> 3) * 4 + (c >> 5)) * 512 + ((kk & 7) * 32 + (c & 31)) * 2; }
; __device__ __forceinline__ int v_rd_base(int lane) { return ((lane & 3) << 3) | (((lane >> 2) & 3) << 6) | (((lane >> 4) & 1) << 5) | (((lane >> 5) & 1) << 8); }
; #define SLOAD(i, k0) do { sr_[i].vs0 = St::ld8(&Vh[(long)((k0) + sr) * LDK + sc]); sr_[i].vs1 = St::ld8(&Vh[(long)((k0) + 32 + sr) * LDK + sc]); \
;     sr_[i].ks0 = St::ld8(&Kh[(long)((k0) + sr) * LDK + sc]); sr_[i].ks1 = St::ld8(&Kh[(long)((k0) + 32 + sr) * LDK + sc]); } while (0)
; template <typename TQ>
; __device__ __forceinline__ void attn_dense_body(const TQ* __restrict__ Qb, const bf16* __restrict__ Kh, const bf16* __restrict__ Vh,
;                                                 unsigned short* __restrict__ Ob, int seq, char* lds, const int wave_s) {
;     ...
;   const int lane = lane_id_asm(), wid = wave_s, tid = wave_s * 64 + lane, r32 = lane & 31, hi = lane >> 5;
;   bf16* V_lds = (bf16*)lds; bf16* K_lds = (bf16*)(lds + 2 * SHM_V);
;   float* ws = (float*)(lds + 2 * SHM_V + 2 * SHM_K) + wid * 64; float* li_l = ws; float* al_l = ws + 32;
;   float m_reg = -1e30f, l_reg = 0; f32x16 o[4] = {}; bf16x8 qr[8];
;   const TQ* Qw = Qb + (long)(wid * QBLK + r32) * LDQ + hi * 8;
; #pragma unroll
;   for (int d0 = 0; d0 < 8; ++d0) qr[d0] = SQ::tobf(SQ::ld8(Qw + d0 * 16));
;   const int sr = tid >> 4, sc = (tid & 15) * 8, vst0 = v_st(sr, sc), vst1 = v_st(32 + sr, sc);
;   const int vb0 = (int)(uintptr_t)V_lds + v_rd_base(lane);
;   struct { typename St::T vs0, vs1, ks0, ks1; } sr_[SDEPTH];
;     ...
;   f32x16 pA0, pA1, pB0, pB1; float mnA, mnB, alA, alB; bf16x8 pa0, pa1, pa2, pa3; const int NT = seq / KVBLK;
;   constexpr int SE = 0, SO = SDEPTH - 1;
;   SLOAD(SE, 0); asm volatile("s_waitcnt vmcnt(0)" ::: "memory"); SWRITE(0, SE); __syncthreads();
;   qkt(pA0, pA1, K_lds, qr, r32, hi); partialSM(pA0, pA1, m_reg, mnA, alA);
.LBB0_574:
	s_mul_i32 s39, s2, 0xc00
	s_mul_hi_u32 s38, s2, 0xc00
	s_add_u32 s45, s6, s39
	s_addc_u32 s47, s7, s38
	s_lshl_b32 s38, s42, 7
	s_ashr_i32 s39, s38, 31
	s_lshl_b64 s[42:43], s[38:39], 1
	s_add_u32 s46, s45, s42
	s_addc_u32 s47, s47, s43
	s_lshl_b64 s[38:39], s[40:41], 1
	s_add_u32 s50, s6, s38
	s_addc_u32 s51, s7, s39
	s_lshl_b32 s44, s44, 7
	s_ashr_i32 s45, s44, 31
	s_lshl_b64 s[38:39], s[44:45], 1
	s_add_u32 s38, s50, s38
	v_readlane_b32 s50, v255, 42
	v_mbcnt_lo_u32_b32 v68, -1, 0
	v_mbcnt_hi_u32_b32 v68, -1, v68
	s_addc_u32 s39, s51, s39
	v_lshlrev_b32_e32 v64, 3, v68
	v_add_u32_e32 v20, s50, v68
	v_ashrrev_i32_e32 v69, 4, v20
	v_add_u32_e32 v21, 32, v69
	v_and_b32_e32 v70, 0x78, v64
	v_mad_i64_i32 v[0:1], s[50:51], v69, s97, 0
	v_mad_i64_i32 v[4:5], s[50:51], v21, s97, 0
	v_or_b32_e32 v0, v0, v70
	v_or_b32_e32 v4, v4, v70
	v_lshl_add_u64 v[8:9], v[0:1], 1, s[38:39]
	v_lshl_add_u64 v[12:13], v[4:5], 1, s[38:39]
	global_load_dwordx4 v[0:3], v[8:9], off offset:2560
	global_load_dwordx4 v[4:7], v[12:13], off offset:2560
	s_nop 0
	global_load_dwordx4 v[8:11], v[8:9], off offset:2048
	s_nop 0
	global_load_dwordx4 v[12:15], v[12:13], off offset:2048
	v_and_b32_e32 v178, 31, v68
	v_readlane_b32 s50, v255, 43
	v_ashrrev_i32_e32 v179, 5, v68
	v_mov_b64_e32 v[16:17], s[46:47]
	v_or_b32_e32 v18, s50, v178
	v_mad_i64_i32 v[16:17], s[46:47], v18, s33, v[16:17]
	v_lshlrev_b32_e32 v18, 3, v179
	v_ashrrev_i32_e32 v19, 31, v18
	v_lshl_add_u64 v[16:17], v[18:19], 1, v[16:17]
	global_load_dwordx4 v[112:115], v[16:17], off
	global_load_dwordx4 v[108:111], v[16:17], off offset:32
	global_load_dwordx4 v[120:123], v[16:17], off offset:64
	global_load_dwordx4 v[124:127], v[16:17], off offset:96
	global_load_dwordx4 v[116:119], v[16:17], off offset:128
	global_load_dwordx4 v[104:107], v[16:17], off offset:160
	global_load_dwordx4 v[100:103], v[16:17], off offset:192
	global_load_dwordx4 v[96:99], v[16:17], off offset:224
	v_and_b32_e32 v19, 0x70, v20
	v_and_b32_e32 v20, 0xfffff0, v69
	v_lshlrev_b32_e32 v22, 1, v69
	v_lshrrev_b32_e32 v23, 1, v69
	v_and_b32_e32 v24, 3, v69
	v_and_or_b32 v20, v69, 8, v20
	v_and_or_b32 v22, v69, 4, v24
	v_and_b32_e32 v24, 0xfffff0, v21
	v_lshlrev_b32_e32 v28, 1, v21
	v_bfe_u32 v18, v64, 5, 2
	v_lshlrev_b32_e32 v25, 1, v70
	v_lshlrev_b32_e32 v26, 8, v69
	v_lshlrev_b32_e32 v21, 8, v21
	v_lshrrev_b32_e32 v20, 1, v20
	v_and_or_b32 v24, v69, 8, v24
	v_lshlrev_b32_e32 v48, 4, v68
	v_bitop3_b32 v26, v25, v26, v19 bitop3:0xde
	v_bitop3_b32 v19, v21, v25, v19 bitop3:0xf6
	v_or_b32_e32 v20, v20, v18
	v_lshrrev_b32_e32 v21, 1, v24
	v_lshlrev_b32_e32 v180, 4, v179
	v_lshlrev_b32_e32 v65, 8, v178
	v_and_b32_e32 v66, 0x70, v48
	v_and_b32_e32 v23, 48, v25
	v_lshlrev_b32_e32 v22, 6, v22
	v_add_u32_e32 v186, 0x8000, v19
	v_lshlrev_b32_e32 v19, 9, v20
	v_or_b32_e32 v18, v21, v18
	v_xad_u32 v27, v66, v180, v65
	v_or3_b32 v19, v19, v22, v23
	v_lshlrev_b32_e32 v18, 9, v18
	v_or3_b32 v18, v18, v22, v23
	v_add_u32_e32 v187, 0, v19
	v_add_u32_e32 v189, 0x8000, v27
	v_add_u32_e32 v185, 0x8000, v26
	v_add_u32_e32 v188, 0, v18
	s_waitcnt vmcnt(0)
	v_readlane_b32 s51, v255, 44
	s_cmp_lg_u32 0, -1
	s_cselect_b32 s51, 0, 0
	s_mov_b32 s81, s80
	s_mov_b32 s82, s80
	s_mov_b32 s83, s80
	s_mov_b32 s84, s80
	s_mov_b32 s85, s80
	s_mov_b32 s86, s80
	s_mov_b32 s87, s80
	s_mov_b32 s88, s80
	s_mov_b32 s89, s80
	s_mov_b32 s90, s80
	s_waitcnt vmcnt(11)
	ds_write_b128 v187, v[0:3]
	s_waitcnt vmcnt(10)
	ds_write_b128 v187, v[4:7] offset:8192
	s_waitcnt vmcnt(9)
	ds_write_b128 v185, v[8:11] offset:32768
	s_waitcnt vmcnt(8)
	ds_write_b128 v185, v[12:15] offset:40960
	s_waitcnt lgkmcnt(0)
	s_barrier
	ds_read_b128 v[0:3], v189 offset:32768
	ds_read_b128 v[4:7], v189 offset:40960
	s_waitcnt vmcnt(7) lgkmcnt(1)
	v_mfma_f32_32x32x16_bf16 v[16:31], v[0:3], v[112:115], 0
	v_add_u32_e32 v0, 32, v180
	v_xad_u32 v0, v0, v66, v65
	v_add_u32_e32 v199, 0x8000, v0
	v_add_u32_e32 v8, 0xc0, v180
	v_xad_u32 v12, v8, v66, v65
	v_add_u32_e32 v201, 0x8000, v12
	v_lshlrev_b32_e32 v10, 1, v68
	s_waitcnt lgkmcnt(0)
	v_mfma_f32_32x32x16_bf16 v[32:47], v[4:7], v[112:115], 0
	ds_read_b128 v[0:3], v199 offset:32768
	ds_read_b128 v[4:7], v199 offset:40960
	s_mov_b32 s91, s80
	s_mov_b32 s92, s80
	s_mov_b32 s93, s80
	s_mov_b32 s94, s80
	s_mov_b32 s95, s80
	s_mov_b32 s50, 2
	s_waitcnt vmcnt(6) lgkmcnt(1)
	v_mfma_f32_32x32x16_bf16 v[16:31], v[0:3], v[108:111], v[16:31]
	v_add_u32_e32 v0, 64, v180
	v_xad_u32 v0, v0, v66, v65
	v_add_u32_e32 v192, 0x8000, v0
	v_lshl_add_u32 v181, v178, 2, s1
	v_mov_b32_e32 v182, 0
	s_waitcnt lgkmcnt(0)
	v_mfma_f32_32x32x16_bf16 v[32:47], v[4:7], v[108:111], v[32:47]
	ds_read_b128 v[0:3], v192 offset:32768
	ds_read_b128 v[4:7], v192 offset:40960
	s_waitcnt vmcnt(5) lgkmcnt(1)
	v_mfma_f32_32x32x16_bf16 v[16:31], v[0:3], v[120:123], v[16:31]
	v_add_u32_e32 v0, 0x60, v180
	v_xad_u32 v0, v0, v66, v65
	v_add_u32_e32 v191, 0x8000, v0
	s_waitcnt lgkmcnt(0)
	v_mfma_f32_32x32x16_bf16 v[32:47], v[4:7], v[120:123], v[32:47]
	ds_read_b128 v[0:3], v191 offset:32768
	ds_read_b128 v[4:7], v191 offset:40960
	s_waitcnt vmcnt(4) lgkmcnt(1)
	v_mfma_f32_32x32x16_bf16 v[16:31], v[0:3], v[124:127], v[16:31]
	v_add_u32_e32 v0, 0x80, v180
	v_xad_u32 v0, v0, v66, v65
	v_add_u32_e32 v190, 0x8000, v0
	ds_read_b128 v[0:3], v189 offset:32896
	s_waitcnt lgkmcnt(1)
	v_mfma_f32_32x32x16_bf16 v[32:47], v[4:7], v[124:127], v[32:47]
	ds_read_b128 v[4:7], v189 offset:41088
	s_waitcnt vmcnt(3) lgkmcnt(1)
	v_mfma_f32_32x32x16_bf16 v[16:31], v[0:3], v[116:119], v[16:31]
	v_and_b32_e32 v0, 0xc0, v48
	v_and_or_b32 v11, v64, 24, v0
	v_add_u32_e32 v0, 0xa0, v180
	v_xad_u32 v0, v0, v66, v65
	v_add_u32_e32 v198, 0x8000, v0
	ds_read_b128 v[0:3], v199 offset:32896
	s_waitcnt lgkmcnt(1)
; #define SLOAD(i, k0) do { sr_[i].vs0 = St::ld8(&Vh[(long)((k0) + sr) * LDK + sc]); sr_[i].vs1 = St::ld8(&Vh[(long)((k0) + 32 + sr) * LDK + sc]); \
;     sr_[i].ks0 = St::ld8(&Kh[(long)((k0) + sr) * LDK + sc]); sr_[i].ks1 = St::ld8(&Kh[(long)((k0) + 32 + sr) * LDK + sc]); } while (0)
; #define SWAIT() do { if constexpr (SDEPTH == 2) asm volatile("s_waitcnt vmcnt(4)" ::: "memory"); else asm volatile("s_waitcnt vmcnt(0)" ::: "memory"); } while (0)
; __device__ __forceinline__ void partialSM(f32x16& p0, f32x16& p1, float& m_reg, float& mn, float& alpha) {
;   constexpr float C = SCALE * 1.4426950408889634f;
;   float pmax = p0[0]; for (int r = 1; r < 16; ++r) pmax = fmaxf(pmax, p0[r]); for (int r = 0; r < 16; ++r) pmax = fmaxf(pmax, p1[r]);
;   { auto rr = __builtin_amdgcn_permlane32_swap(__float_as_uint(pmax), __float_as_uint(pmax), false, false);
;     pmax = fmaxf(__uint_as_float(rr[0]), __uint_as_float(rr[1])); }
;   if (__builtin_expect(__all(pmax - m_reg <= THR / SCALE), 1)) { mn = m_reg; alpha = 1.f; }
;   else { mn = fmaxf(m_reg, pmax); alpha = __builtin_amdgcn_exp2f((m_reg - mn) * C); m_reg = mn; }
;   float mnC = -mn * C;
;   for (int r = 0; r < 16; ++r) p0[r] = fmaf(p0[r], C, mnC); for (int r = 0; r < 16; ++r) p1[r] = fmaf(p1[r], C, mnC);
;   for (int r = 0; r < 16; ++r) p0[r] = __builtin_amdgcn_exp2f(p0[r]);
; template <typename TQ>
; __device__ __forceinline__ void attn_dense_body(const TQ* __restrict__ Qb, const bf16* __restrict__ Kh, const bf16* __restrict__ Vh,
;                                                 unsigned short* __restrict__ Ob, int seq, char* lds, const int wave_s) {
;     ...
;   qkt(pA0, pA1, K_lds, qr, r32, hi); partialSM(pA0, pA1, m_reg, mnA, alA);
;   SLOAD(SO, KVBLK); if constexpr (SDEPTH == 2) { if (2 < NT) SLOAD(SE, 2 * KVBLK); }
;   SWAIT(); SWRITE(1, SO); __syncthreads();
	v_mfma_f32_32x32x16_bf16 v[32:47], v[4:7], v[116:119], v[32:47]
	v_add_u32_e32 v4, 64, v69
	v_mad_i64_i32 v[4:5], s[46:47], v4, s97, 0
	v_or_b32_e32 v4, v4, v70
	v_lshl_add_u64 v[8:9], v[4:5], 1, s[38:39]
	ds_read_b128 v[4:7], v199 offset:41088
	global_load_dwordx4 v[48:51], v[8:9], off offset:2560
	s_waitcnt vmcnt(3) lgkmcnt(1)
	v_mfma_f32_32x32x16_bf16 v[16:31], v[0:3], v[104:107], v[16:31]
	v_add_u32_e32 v0, 0x60, v69
	v_mad_i64_i32 v[0:1], s[46:47], v0, s97, 0
	v_or_b32_e32 v0, v0, v70
	v_lshl_add_u64 v[0:1], v[0:1], 1, s[38:39]
	global_load_dwordx4 v[52:55], v[0:1], off offset:2560
	global_load_dwordx4 v[56:59], v[8:9], off offset:2048
	global_load_dwordx4 v[60:63], v[0:1], off offset:2048
	ds_read_b128 v[0:3], v192 offset:32896
	s_waitcnt lgkmcnt(1)
	v_mfma_f32_32x32x16_bf16 v[32:47], v[4:7], v[104:107], v[32:47]
	v_and_b32_e32 v4, 32, v10
	v_and_b32_e32 v5, 0x100, v64
	v_or3_b32 v71, v11, v4, v5
	ds_read_b128 v[4:7], v192 offset:41088
	v_add_u32_e32 v184, s51, v71
	s_waitcnt vmcnt(5) lgkmcnt(1)
	v_mfma_f32_32x32x16_bf16 v[16:31], v[0:3], v[100:103], v[16:31]
	v_add_u32_e32 v0, 0xe0, v180
	v_xad_u32 v0, v0, v66, v65
	v_add_u32_e32 v200, 0x8000, v0
	ds_read_b128 v[0:3], v191 offset:32896
	ds_read_b128 v[64:67], v191 offset:41088
	s_waitcnt lgkmcnt(2)
	v_mfma_f32_32x32x16_bf16 v[32:47], v[4:7], v[100:103], v[32:47]
	s_waitcnt vmcnt(4) lgkmcnt(1)
	v_mfma_f32_32x32x16_bf16 v[16:31], v[0:3], v[96:99], v[16:31]
	v_mov_b64_e32 v[0:1], s[80:81]
	v_mov_b64_e32 v[14:15], s[94:95]
	v_mov_b64_e32 v[2:3], s[82:83]
	v_mov_b64_e32 v[4:5], s[84:85]
	v_mov_b64_e32 v[6:7], s[86:87]
	v_mov_b64_e32 v[8:9], s[88:89]
	v_mov_b64_e32 v[10:11], s[90:91]
	s_waitcnt lgkmcnt(0)
	v_mfma_f32_32x32x16_bf16 v[32:47], v[64:67], v[96:99], v[32:47]
	s_nop 2
	v_max_f32_e32 v64, v17, v17
	v_max_f32_e32 v65, v16, v16
	v_max_f32_e32 v64, v65, v64
	v_max3_f32 v64, v64, v18, v19
	v_max3_f32 v64, v64, v20, v21
	v_max3_f32 v64, v64, v22, v23
	v_max3_f32 v64, v64, v24, v25
	v_max3_f32 v64, v64, v26, v27
	v_max3_f32 v64, v64, v28, v29
	v_max3_f32 v64, v64, v30, v31
	v_max3_f32 v64, v64, v32, v33
	v_max3_f32 v64, v64, v34, v35
	v_max3_f32 v64, v64, v36, v37
	v_max3_f32 v64, v64, v38, v39
	v_max3_f32 v64, v64, v40, v41
	v_max3_f32 v64, v64, v42, v43
	v_max3_f32 v64, v64, v44, v45
	v_max3_f32 v64, v64, v46, v47
	v_mov_b32_e32 v65, v64
	s_nop 1
	v_permlane32_swap_b32_e32 v64, v65
	v_max_f32_e32 v73, v64, v64
	v_add_u32_e32 v64, 0x80, v69
	v_max_f32_e32 v72, v65, v65
	v_mad_i64_i32 v[64:65], s[46:47], v64, s97, 0
	v_add_u32_e32 v66, 0xa0, v69
	v_or_b32_e32 v64, v64, v70
	v_mad_i64_i32 v[66:67], s[46:47], v66, s97, 0
	v_lshl_add_u64 v[64:65], v[64:65], 1, s[38:39]
	v_or_b32_e32 v66, v66, v70
	v_lshl_add_u64 v[66:67], v[66:67], 1, s[38:39]
	global_load_dwordx4 v[128:131], v[64:65], off offset:2560
	global_load_dwordx4 v[132:135], v[64:65], off offset:2048
	global_load_dwordx4 v[136:139], v[66:67], off offset:2560
	global_load_dwordx4 v[140:143], v[66:67], off offset:2048
	v_max_f32_e32 v64, v73, v72
	s_waitcnt vmcnt(4)
	s_waitcnt vmcnt(7)
	ds_write_b128 v187, v[48:51] offset:16384
	s_waitcnt vmcnt(6)
	ds_write_b128 v187, v[52:55] offset:24576
	s_waitcnt vmcnt(5)
	ds_write_b128 v185, v[56:59] offset:49152
	s_waitcnt vmcnt(4)
	ds_write_b128 v185, v[60:63] offset:57344
	v_xor_b32_e32 v185, 0x18000, v185
	v_xor_b32_e32 v187, 0x8000, v187
	v_max_f32_e32 v48, 0xf149f2ca, v64
	v_sub_f32_e32 v49, 0xf149f2ca, v48
	v_mul_f32_e32 v49, 0x3e0293ee, v49
	v_add_f32_e32 v65, 0x7149f2ca, v64
	v_exp_f32_e32 v49, v49
	v_cmp_ge_f32_e32 vcc, s9, v65
	s_cmp_eq_u64 vcc, exec
	s_cselect_b64 vcc, -1, 0
	v_cndmask_b32_e64 v202, v49, 1.0, vcc
	v_mov_b32_e32 v49, 0xf149f2ca
	v_cndmask_b32_e32 v164, v48, v49, vcc
	v_mul_f32_e32 v48, 0xbe0293ee, v164
	v_fmamk_f32 v16, v16, 0x3e0293ee, v48
	v_exp_f32_e32 v161, v16
	v_fmamk_f32 v16, v17, 0x3e0293ee, v48
	v_exp_f32_e32 v175, v16
	v_fmamk_f32 v16, v18, 0x3e0293ee, v48
	v_exp_f32_e32 v162, v16
	v_fmamk_f32 v16, v19, 0x3e0293ee, v48
	v_exp_f32_e32 v206, v16
	v_fmamk_f32 v16, v20, 0x3e0293ee, v48
	v_exp_f32_e32 v174, v16
	v_fmamk_f32 v16, v21, 0x3e0293ee, v48
	v_exp_f32_e32 v209, v16
	v_fmamk_f32 v16, v22, 0x3e0293ee, v48
	v_exp_f32_e32 v163, v16
	v_fmamk_f32 v16, v23, 0x3e0293ee, v48
	v_exp_f32_e32 v173, v16
	v_fmamk_f32 v16, v24, 0x3e0293ee, v48
	v_exp_f32_e32 v169, v16
	v_fmamk_f32 v16, v25, 0x3e0293ee, v48
	v_exp_f32_e32 v171, v16
	v_fmamk_f32 v16, v26, 0x3e0293ee, v48
	v_exp_f32_e32 v170, v16
	v_fmamk_f32 v16, v27, 0x3e0293ee, v48
	s_addk_i32 s51, 0x4000
	v_exp_f32_e32 v172, v16
	v_fmamk_f32 v16, v28, 0x3e0293ee, v48
	s_add_u32 s40, s40, s44
	v_exp_f32_e32 v165, v16
	v_fmamk_f32 v16, v29, 0x3e0293ee, v48
	s_addc_u32 s41, s41, s45
	v_pk_fma_f32 v[144:145], v[46:47], s[30:31], v[48:49] op_sel_hi:[1,0,0]
	v_pk_fma_f32 v[150:151], v[44:45], s[30:31], v[48:49] op_sel_hi:[1,0,0]
	v_pk_fma_f32 v[154:155], v[42:43], s[30:31], v[48:49] op_sel_hi:[1,0,0]
	v_pk_fma_f32 v[146:147], v[40:41], s[30:31], v[48:49] op_sel_hi:[1,0,0]
	v_pk_fma_f32 v[148:149], v[38:39], s[30:31], v[48:49] op_sel_hi:[1,0,0]
	v_pk_fma_f32 v[152:153], v[36:37], s[30:31], v[48:49] op_sel_hi:[1,0,0]
	v_pk_fma_f32 v[156:157], v[34:35], s[30:31], v[48:49] op_sel_hi:[1,0,0]
	v_pk_fma_f32 v[158:159], v[32:33], s[30:31], v[48:49] op_sel_hi:[1,0,0]
	v_exp_f32_e32 v167, v16
	v_fmamk_f32 v16, v30, 0x3e0293ee, v48
	v_fmac_f32_e32 v48, 0x3e0293ee, v31
	s_lshl_b64 s[40:41], s[40:41], 1
	v_readlane_b32 s44, v255, 53
	v_exp_f32_e32 v166, v16
	v_exp_f32_e32 v168, v48
	v_mad_i64_i32 v[16:17], s[46:47], v69, s33, 0
	v_and_b32_e32 v18, 15, v68
	s_add_u32 s40, s44, s40
	v_readlane_b32 s44, v255, 54
	v_lshl_or_b32 v16, v18, 4, v16
	s_addc_u32 s41, s44, s41
	v_mov_b64_e32 v[12:13], s[92:93]
	v_mov_b32_e32 v176, v16
	s_add_u32 s52, s40, 0xfffb8000
	s_addc_u32 s53, s41, -1
	v_mov_b64_e32 v[62:63], v[14:15]
	v_mov_b64_e32 v[46:47], v[14:15]
	v_mov_b64_e32 v[30:31], v[14:15]
	v_cmp_gt_u32_e64 s[38:39], 32, v68
	v_add_u32_e32 v183, s51, v71
	v_mov_b64_e32 v[60:61], v[12:13]
	v_mov_b64_e32 v[58:59], v[10:11]
	v_mov_b64_e32 v[56:57], v[8:9]
	v_mov_b64_e32 v[54:55], v[6:7]
	v_mov_b64_e32 v[52:53], v[4:5]
	v_mov_b64_e32 v[50:51], v[2:3]
	v_mov_b64_e32 v[48:49], v[0:1]
	v_mov_b64_e32 v[44:45], v[12:13]
	v_mov_b64_e32 v[42:43], v[10:11]
	v_mov_b64_e32 v[40:41], v[8:9]
	v_mov_b64_e32 v[38:39], v[6:7]
	v_mov_b64_e32 v[36:37], v[4:5]
	v_mov_b64_e32 v[34:35], v[2:3]
	v_mov_b64_e32 v[32:33], v[0:1]
	v_mov_b64_e32 v[28:29], v[12:13]
	v_mov_b64_e32 v[26:27], v[10:11]
	v_mov_b64_e32 v[24:25], v[8:9]
	v_mov_b64_e32 v[22:23], v[6:7]
	v_mov_b64_e32 v[20:21], v[4:5]
	v_mov_b64_e32 v[18:19], v[2:3]
	v_mov_b64_e32 v[16:17], v[0:1]
	s_mov_b64 s[94:95], s[16:17]
	s_mov_b64 s[84:85], s[12:13]
	s_waitcnt lgkmcnt(0)
	s_barrier
; #define SBAR() __builtin_amdgcn_sched_barrier(0)
; #define SLOAD(i, k0) do { sr_[i].vs0 = St::ld8(&Vh[(long)((k0) + sr) * LDK + sc]); sr_[i].vs1 = St::ld8(&Vh[(long)((k0) + 32 + sr) * LDK + sc]); \
;     sr_[i].ks0 = St::ld8(&Kh[(long)((k0) + sr) * LDK + sc]); sr_[i].ks1 = St::ld8(&Kh[(long)((k0) + 32 + sr) * LDK + sc]); } while (0)
; __device__ __forceinline__ void finishSM(f32x16& p0, f32x16& p1, float alpha, float& l_reg, bf16x8& pa0, bf16x8& pa1, bf16x8& pa2, bf16x8& pa3) {
;   for (int r = 0; r < 16; ++r) p1[r] = __builtin_amdgcn_exp2f(p1[r]);
;   float ps = 0; for (int r = 0; r < 16; ++r) ps += p0[r]; for (int r = 0; r < 16; ++r) ps += p1[r];
;   { auto rr = __builtin_amdgcn_permlane32_swap(__float_as_uint(ps), __float_as_uint(ps), false, false);
;     ps = __uint_as_float(rr[0]) + __uint_as_float(rr[1]); }
;   l_reg = l_reg * alpha + ps;
;     ...
;   PK4(p0, 0, pa0); PK4(p0, 8, pa1); PK4(p1, 0, pa2); PK4(p1, 8, pa3);
; template <typename TQ>
; __device__ __forceinline__ void attn_dense_body(const TQ* __restrict__ Qb, const bf16* __restrict__ Kh, const bf16* __restrict__ Vh,
;                                                 unsigned short* __restrict__ Ob, int seq, char* lds, const int wave_s) {
;     ...
;     SBAR(); qkt(pB0, pB1, (bf16*)((char*)K_lds + SHM_K), qr, r32, hi);
;     finishSM(pA0, pA1, alA, l_reg, pa0, pa1, pa2, pa3); SBAR();
;     SLOAD(SO, (j + SDEPTH) * KVBLK); SBAR();
;     pv_d0(o, vb0, pa0, pa1, pa2, pa3); partialSM(pB0, pB1, m_reg, mnB, alB);
.LBB0_575:
	ds_read_b128 v[64:67], v189 offset:49152
	ds_read_b128 v[68:71], v189 offset:57344
	ds_read_b128 v[210:213], v199 offset:49152
	ds_read_b128 v[214:217], v199 offset:57344
	ds_read_b128 v[240:243], v192 offset:49152
	ds_read_b128 v[244:247], v192 offset:57344
	v_add_f32_e32 v160, 0, v161
	v_add_f32_e32 v160, v175, v160
	s_waitcnt lgkmcnt(5)
	v_mfma_f32_32x32x16_bf16 v[80:95], v[64:67], v[112:115], 0
	v_add_f32_e32 v160, v162, v160
	v_add_f32_e32 v160, v206, v160
	v_add_f32_e32 v160, v174, v160
	v_add_f32_e32 v160, v209, v160
	v_add_f32_e32 v160, v163, v160
	v_add_f32_e32 v160, v173, v160
	v_add_f32_e32 v160, v169, v160
	s_waitcnt lgkmcnt(4)
	v_mfma_f32_32x32x16_bf16 v[64:79], v[68:71], v[112:115], 0
	v_add_f32_e32 v160, v171, v160
	v_add_f32_e32 v160, v170, v160
	v_add_f32_e32 v160, v172, v160
	v_exp_f32_e32 v158, v158
	v_add_f32_e32 v160, v165, v160
	v_exp_f32_e32 v159, v159
	v_add_f32_e32 v160, v167, v160
	s_waitcnt lgkmcnt(3)
	v_mfma_f32_32x32x16_bf16 v[80:95], v[210:213], v[108:111], v[80:95]
	v_exp_f32_e32 v156, v156
	v_add_f32_e32 v160, v166, v160
	v_exp_f32_e32 v157, v157
	v_add_f32_e32 v160, v168, v160
	v_exp_f32_e32 v152, v152
	v_add_f32_e32 v160, v158, v160
	v_exp_f32_e32 v153, v153
	s_waitcnt lgkmcnt(2)
	v_mfma_f32_32x32x16_bf16 v[64:79], v[214:217], v[108:111], v[64:79]
	ds_read_b128 v[210:213], v191 offset:49152
	ds_read_b128 v[214:217], v191 offset:57344
	v_add_f32_e32 v160, v159, v160
	v_exp_f32_e32 v148, v148
	v_add_f32_e32 v160, v156, v160
	v_exp_f32_e32 v149, v149
	v_add_f32_e32 v160, v157, v160
	v_exp_f32_e32 v146, v146
	s_waitcnt lgkmcnt(3)
	v_mfma_f32_32x32x16_bf16 v[80:95], v[240:243], v[120:123], v[80:95]
	v_add_f32_e32 v160, v152, v160
	v_exp_f32_e32 v147, v147
	v_add_f32_e32 v160, v153, v160
	v_exp_f32_e32 v154, v154
	v_add_f32_e32 v160, v148, v160
	v_exp_f32_e32 v155, v155
	v_add_f32_e32 v160, v149, v160
	s_waitcnt lgkmcnt(2)
	v_mfma_f32_32x32x16_bf16 v[64:79], v[244:247], v[120:123], v[64:79]
	ds_read_b128 v[240:243], v189 offset:49280
	ds_read_b128 v[244:247], v189 offset:57472
	v_exp_f32_e32 v150, v150
	v_add_f32_e32 v160, v146, v160
	v_exp_f32_e32 v151, v151
	v_add_f32_e32 v160, v147, v160
	v_exp_f32_e32 v144, v144
	v_add_f32_e32 v160, v154, v160
	s_waitcnt lgkmcnt(3)
	v_mfma_f32_32x32x16_bf16 v[80:95], v[210:213], v[124:127], v[80:95]
	v_exp_f32_e32 v145, v145
	v_add_f32_e32 v160, v155, v160
	v_add_f32_e32 v160, v150, v160
	v_add_f32_e32 v160, v151, v160
	v_add_f32_e32 v160, v144, v160
	v_add_f32_e32 v203, v145, v160
	v_mov_b32_e32 v204, v203
	s_waitcnt lgkmcnt(2)
	v_mfma_f32_32x32x16_bf16 v[64:79], v[214:217], v[124:127], v[64:79]
	ds_read_b128 v[210:213], v199 offset:49280
	ds_read_b128 v[214:217], v199 offset:57472
	v_permlane32_swap_b32_e32 v203, v204
	s_waitcnt lgkmcnt(3)
	v_mfma_f32_32x32x16_bf16 v[80:95], v[240:243], v[116:119], v[80:95]
	s_waitcnt lgkmcnt(2)
	v_mfma_f32_32x32x16_bf16 v[64:79], v[244:247], v[116:119], v[64:79]
	ds_read_b128 v[240:243], v192 offset:49280
	ds_read_b128 v[244:247], v192 offset:57472
	s_waitcnt lgkmcnt(3)
	v_mfma_f32_32x32x16_bf16 v[80:95], v[210:213], v[104:107], v[80:95]
	s_waitcnt lgkmcnt(2)
	v_mfma_f32_32x32x16_bf16 v[64:79], v[214:217], v[104:107], v[64:79]
	ds_read_b128 v[210:213], v191 offset:49280
	ds_read_b128 v[214:217], v191 offset:57472
	s_waitcnt lgkmcnt(3)
	v_mfma_f32_32x32x16_bf16 v[80:95], v[240:243], v[100:103], v[80:95]
	s_waitcnt lgkmcnt(2)
	v_mfma_f32_32x32x16_bf16 v[64:79], v[244:247], v[100:103], v[64:79]
	v_cvt_pk_bf16_f32 v160, v161, v175
	v_cvt_pk_bf16_f32 v161, v162, v206
	v_cvt_pk_bf16_f32 v162, v174, v209
	v_cvt_pk_bf16_f32 v163, v163, v173
	v_cvt_pk_bf16_f32 v206, v169, v171
	v_cvt_pk_bf16_f32 v207, v170, v172
	s_waitcnt lgkmcnt(1)
	v_mfma_f32_32x32x16_bf16 v[80:95], v[210:213], v[96:99], v[80:95]
	v_cvt_pk_bf16_f32 v208, v165, v167
	v_cvt_pk_bf16_f32 v209, v166, v168
	v_cvt_pk_bf16_f32 v166, v158, v159
	v_cvt_pk_bf16_f32 v167, v156, v157
	v_cvt_pk_bf16_f32 v168, v152, v153
	s_waitcnt lgkmcnt(0)
	v_mfma_f32_32x32x16_bf16 v[64:79], v[214:217], v[96:99], v[64:79]
	v_cvt_pk_bf16_f32 v169, v148, v149
	v_cvt_pk_bf16_f32 v170, v146, v147
	v_cvt_pk_bf16_f32 v171, v154, v155
	v_cvt_pk_bf16_f32 v172, v150, v151
	v_cvt_pk_bf16_f32 v173, v144, v145
	global_load_dwordx4 v[144:147], v176, s[52:53]
	global_load_dwordx4 v[148:151], v176, s[52:53] offset:-512
	s_add_u32 s52, s52, 0x18000
	s_addc_u32 s53, s53, 0
	global_load_dwordx4 v[156:159], v176, s[52:53]
	global_load_dwordx4 v[152:155], v176, s[52:53] offset:-512
	s_add_u32 s52, s52, 0x18000
	s_addc_u32 s53, s53, 0
	ds_read_b64_tr_b16 v[210:211], v184 offset:0
	ds_read_b64_tr_b16 v[212:213], v184 offset:0x800
	ds_read_b64_tr_b16 v[214:215], v184 offset:0x1000
	ds_read_b64_tr_b16 v[216:217], v184 offset:0x1800
	ds_read_b64_tr_b16 v[224:225], v184 offset:0x2000
	ds_read_b64_tr_b16 v[226:227], v184 offset:0x2800
	ds_read_b64_tr_b16 v[228:229], v184 offset:0x3000
	ds_read_b64_tr_b16 v[230:231], v184 offset:0x3800
	s_waitcnt lgkmcnt(0)
	s_nop 0
	v_mfma_f32_32x32x16_bf16 v[0:15], v[160:163], v[210:213], v[0:15]
	ds_read_b64_tr_b16 v[210:211], v184 offset:0x200
	ds_read_b64_tr_b16 v[212:213], v184 offset:0xa00
	v_mfma_f32_32x32x16_bf16 v[0:15], v[206:209], v[214:217], v[0:15]
	ds_read_b64_tr_b16 v[214:215], v184 offset:0x1200
	ds_read_b64_tr_b16 v[216:217], v184 offset:0x1a00
	v_mfma_f32_32x32x16_bf16 v[0:15], v[166:169], v[224:227], v[0:15]
	ds_read_b64_tr_b16 v[224:225], v184 offset:0x2200
	ds_read_b64_tr_b16 v[226:227], v184 offset:0x2a00
	v_mfma_f32_32x32x16_bf16 v[0:15], v[170:173], v[228:231], v[0:15]
	ds_read_b64_tr_b16 v[228:229], v184 offset:0x3200
	ds_read_b64_tr_b16 v[230:231], v184 offset:0x3a00
	s_waitcnt lgkmcnt(0)
; #define SWAIT() do { if constexpr (SDEPTH == 2) asm volatile("s_waitcnt vmcnt(4)" ::: "memory"); else asm volatile("s_waitcnt vmcnt(0)" ::: "memory"); } while (0)
; #define RESC(a) do { if (__any((a) < 1.f)) { if (hi == 0) al_l[r32] = (a); asm volatile("s_waitcnt lgkmcnt(0)" ::: "memory"); \
;     for (int d = 0; d < 4; ++d) for (int r = 0; r < 16; ++r) o[d][r] *= al_l[crow(r, hi)]; } } while (0)
; __device__ __forceinline__ void partialSM(f32x16& p0, f32x16& p1, float& m_reg, float& mn, float& alpha) {
;     ...
;   float pmax = p0[0]; for (int r = 1; r < 16; ++r) pmax = fmaxf(pmax, p0[r]); for (int r = 0; r < 16; ++r) pmax = fmaxf(pmax, p1[r]);
;   { auto rr = __builtin_amdgcn_permlane32_swap(__float_as_uint(pmax), __float_as_uint(pmax), false, false);
;     pmax = fmaxf(__uint_as_float(rr[0]), __uint_as_float(rr[1])); }
;   if (__builtin_expect(__all(pmax - m_reg <= THR / SCALE), 1)) { mn = m_reg; alpha = 1.f; }
;   else { mn = fmaxf(m_reg, pmax); alpha = __builtin_amdgcn_exp2f((m_reg - mn) * C); m_reg = mn; }
; template <typename TQ>
; __device__ __forceinline__ void attn_dense_body(const TQ* __restrict__ Qb, const bf16* __restrict__ Kh, const bf16* __restrict__ Vh,
;                                                 unsigned short* __restrict__ Ob, int seq, char* lds, const int wave_s) {
;     ...
;     pv_d0(o, vb0, pa0, pa1, pa2, pa3); partialSM(pB0, pB1, m_reg, mnB, alB);
;     __syncthreads(); SWAIT(); SWRITE(0, SE);
;     RESC(alB); __syncthreads();
	v_mfma_f32_32x32x16_bf16 v[48:63], v[160:163], v[210:213], v[48:63]
	ds_read_b64_tr_b16 v[210:211], v184 offset:0x400
	ds_read_b64_tr_b16 v[212:213], v184 offset:0xc00
	v_mfma_f32_32x32x16_bf16 v[48:63], v[206:209], v[214:217], v[48:63]
	ds_read_b64_tr_b16 v[214:215], v184 offset:0x1400
	ds_read_b64_tr_b16 v[216:217], v184 offset:0x1c00
	v_mfma_f32_32x32x16_bf16 v[48:63], v[166:169], v[224:227], v[48:63]
	ds_read_b64_tr_b16 v[224:225], v184 offset:0x2400
	ds_read_b64_tr_b16 v[226:227], v184 offset:0x2c00
	v_mfma_f32_32x32x16_bf16 v[48:63], v[170:173], v[228:231], v[48:63]
	ds_read_b64_tr_b16 v[228:229], v184 offset:0x3400
	ds_read_b64_tr_b16 v[230:231], v184 offset:0x3c00
	s_waitcnt lgkmcnt(0)
	v_mfma_f32_32x32x16_bf16 v[32:47], v[160:163], v[210:213], v[32:47]
	ds_read_b64_tr_b16 v[210:211], v184 offset:0x600
	ds_read_b64_tr_b16 v[212:213], v184 offset:0xe00
	v_mfma_f32_32x32x16_bf16 v[32:47], v[206:209], v[214:217], v[32:47]
	ds_read_b64_tr_b16 v[214:215], v184 offset:0x1600
	ds_read_b64_tr_b16 v[216:217], v184 offset:0x1e00
	v_mfma_f32_32x32x16_bf16 v[32:47], v[166:169], v[224:227], v[32:47]
	ds_read_b64_tr_b16 v[224:225], v184 offset:0x2600
	ds_read_b64_tr_b16 v[226:227], v184 offset:0x2e00
	v_mfma_f32_32x32x16_bf16 v[32:47], v[170:173], v[228:231], v[32:47]
	ds_read_b64_tr_b16 v[228:229], v184 offset:0x3600
	ds_read_b64_tr_b16 v[230:231], v184 offset:0x3e00
	s_waitcnt lgkmcnt(0)
	v_mfma_f32_32x32x16_bf16 v[16:31], v[160:163], v[210:213], v[16:31]
	v_max_f32_e32 v160, v80, v81
	v_max3_f32 v160, v160, v82, v83
	v_max3_f32 v160, v160, v84, v85
	v_max3_f32 v160, v160, v86, v87
	v_max3_f32 v160, v160, v88, v89
	v_max3_f32 v160, v160, v90, v91
	v_max3_f32 v160, v160, v92, v93
	v_mfma_f32_32x32x16_bf16 v[16:31], v[206:209], v[214:217], v[16:31]
	v_max3_f32 v160, v160, v94, v95
	v_max3_f32 v160, v160, v64, v65
	v_max3_f32 v160, v160, v66, v67
	v_max3_f32 v160, v160, v68, v69
	v_max3_f32 v160, v160, v70, v71
	v_max3_f32 v160, v160, v72, v73
	v_max3_f32 v160, v160, v74, v75
	v_max3_f32 v160, v160, v76, v77
	v_mfma_f32_32x32x16_bf16 v[16:31], v[166:169], v[224:227], v[16:31]
	v_max3_f32 v160, v160, v78, v79
	v_mov_b32_e32 v161, v160
	s_nop 1
	v_permlane32_swap_b32_e32 v160, v161
	v_max_f32_e32 v160, v160, v161
	v_sub_f32_e32 v161, v160, v164
	v_cmp_ge_f32_e32 vcc, s9, v161
	v_max_f32_e32 v160, v164, v160
	v_mfma_f32_32x32x16_bf16 v[16:31], v[170:173], v[228:231], v[16:31]
	v_sub_f32_e32 v161, v164, v160
	v_mul_f32_e32 v161, 0x3e0293ee, v161
	v_exp_f32_e32 v161, v161
	s_cmp_eq_u64 vcc, exec
	s_cselect_b64 s[40:41], -1, 0
	s_waitcnt vmcnt(4)
	v_cndmask_b32_e64 v205, v161, 1.0, s[40:41]
	v_cmp_gt_f32_e32 vcc, 1.0, v205
	s_waitcnt vmcnt(7)
	ds_write_b128 v187, v[128:131]
	s_waitcnt vmcnt(5)
	ds_write_b128 v187, v[136:139] offset:8192
	ds_write_b128 v185, v[132:135] offset:32768
	s_waitcnt vmcnt(4)
	ds_write_b128 v185, v[140:143] offset:40960
	s_cbranch_vccz .LBB0_579
	s_and_saveexec_b64 s[44:45], s[38:39]
	ds_write_b32 v181, v205 offset:128
	s_or_b64 exec, exec, s[44:45]
	s_waitcnt lgkmcnt(0)
	v_add_u32_e32 v161, s1, v180
	ds_read_b128 v[166:169], v161 offset:224
	ds_read_b128 v[170:173], v161 offset:192
	ds_read_b128 v[206:209], v161 offset:160
	ds_read_b128 v[210:213], v161 offset:128
	s_waitcnt lgkmcnt(3)
	v_pk_mul_f32 v[12:13], v[12:13], v[166:167]
	s_waitcnt lgkmcnt(2)
	v_pk_mul_f32 v[8:9], v[8:9], v[170:171]
	s_waitcnt lgkmcnt(1)
	v_pk_mul_f32 v[4:5], v[4:5], v[206:207]
	v_pk_mul_f32 v[14:15], v[14:15], v[168:169]
	v_pk_mul_f32 v[10:11], v[10:11], v[172:173]
	v_pk_mul_f32 v[6:7], v[6:7], v[208:209]
	s_waitcnt lgkmcnt(0)
	v_pk_mul_f32 v[2:3], v[2:3], v[212:213]
	v_pk_mul_f32 v[0:1], v[0:1], v[210:211]
	v_pk_mul_f32 v[60:61], v[60:61], v[166:167]
	v_pk_mul_f32 v[56:57], v[56:57], v[170:171]
	v_pk_mul_f32 v[52:53], v[52:53], v[206:207]
	v_pk_mul_f32 v[62:63], v[62:63], v[168:169]
	v_pk_mul_f32 v[58:59], v[58:59], v[172:173]
	v_pk_mul_f32 v[54:55], v[54:55], v[208:209]
	v_pk_mul_f32 v[50:51], v[50:51], v[212:213]
	v_pk_mul_f32 v[48:49], v[48:49], v[210:211]
	v_pk_mul_f32 v[44:45], v[44:45], v[166:167]
	v_pk_mul_f32 v[40:41], v[40:41], v[170:171]
	v_pk_mul_f32 v[36:37], v[36:37], v[206:207]
	v_pk_mul_f32 v[46:47], v[46:47], v[168:169]
	v_pk_mul_f32 v[42:43], v[42:43], v[172:173]
	v_pk_mul_f32 v[38:39], v[38:39], v[208:209]
	v_pk_mul_f32 v[34:35], v[34:35], v[212:213]
	v_pk_mul_f32 v[32:33], v[32:33], v[210:211]
	v_pk_mul_f32 v[28:29], v[28:29], v[166:167]
	v_pk_mul_f32 v[24:25], v[24:25], v[170:171]
	v_pk_mul_f32 v[20:21], v[20:21], v[206:207]
	v_pk_mul_f32 v[30:31], v[30:31], v[168:169]
	v_pk_mul_f32 v[26:27], v[26:27], v[172:173]
	v_pk_mul_f32 v[22:23], v[22:23], v[208:209]
	v_pk_mul_f32 v[18:19], v[18:19], v[212:213]
	v_pk_mul_f32 v[16:17], v[16:17], v[210:211]
; #define SBAR() __builtin_amdgcn_sched_barrier(0)
; #define SLOAD(i, k0) do { sr_[i].vs0 = St::ld8(&Vh[(long)((k0) + sr) * LDK + sc]); sr_[i].vs1 = St::ld8(&Vh[(long)((k0) + 32 + sr) * LDK + sc]); \
;     sr_[i].ks0 = St::ld8(&Kh[(long)((k0) + sr) * LDK + sc]); sr_[i].ks1 = St::ld8(&Kh[(long)((k0) + 32 + sr) * LDK + sc]); } while (0)
; #define RESC(a) do { if (__any((a) < 1.f)) { if (hi == 0) al_l[r32] = (a); asm volatile("s_waitcnt lgkmcnt(0)" ::: "memory"); \
;     for (int d = 0; d < 4; ++d) for (int r = 0; r < 16; ++r) o[d][r] *= al_l[crow(r, hi)]; } } while (0)
; __device__ __forceinline__ void partialSM(f32x16& p0, f32x16& p1, float& m_reg, float& mn, float& alpha) {
;     ...
;   float mnC = -mn * C;
;   for (int r = 0; r < 16; ++r) p0[r] = fmaf(p0[r], C, mnC); for (int r = 0; r < 16; ++r) p1[r] = fmaf(p1[r], C, mnC);
;   for (int r = 0; r < 16; ++r) p0[r] = __builtin_amdgcn_exp2f(p0[r]);
; }
; __device__ __forceinline__ void finishSM(f32x16& p0, f32x16& p1, float alpha, float& l_reg, bf16x8& pa0, bf16x8& pa1, bf16x8& pa2, bf16x8& pa3) {
;   for (int r = 0; r < 16; ++r) p1[r] = __builtin_amdgcn_exp2f(p1[r]);
;   float ps = 0; for (int r = 0; r < 16; ++r) ps += p0[r]; for (int r = 0; r < 16; ++r) ps += p1[r];
;   { auto rr = __builtin_amdgcn_permlane32_swap(__float_as_uint(ps), __float_as_uint(ps), false, false);
;     ps = __uint_as_float(rr[0]) + __uint_as_float(rr[1]); }
;   l_reg = l_reg * alpha + ps;
; template <typename TQ>
; __device__ __forceinline__ void attn_dense_body(const TQ* __restrict__ Qb, const bf16* __restrict__ Kh, const bf16* __restrict__ Vh,
;                                                 unsigned short* __restrict__ Ob, int seq, char* lds, const int wave_s) {
;     ...
;     RESC(alB); __syncthreads();
;     SBAR(); qkt(pA0, pA1, K_lds, qr, r32, hi);
;     finishSM(pB0, pB1, alB, l_reg, pa0, pa1, pa2, pa3); SBAR();
;     if (SDEPTH == 1 || j + 3 < NT) SLOAD(SE, (j + 1 + SDEPTH) * KVBLK); SBAR();
.LBB0_579:
	v_xor_b32_e32 v189, 0x18000, v189
	v_xor_b32_e32 v199, 0x18000, v199
	v_xor_b32_e32 v192, 0x18000, v192
	v_xor_b32_e32 v191, 0x18000, v191
	v_cndmask_b32_e64 v206, v160, v164, s[40:41]
	v_mul_f32_e32 v207, 0xbe0293ee, v206
	v_fmamk_f32 v80, v80, 0x3e0293ee, v207
	v_fmamk_f32 v81, v81, 0x3e0293ee, v207
	v_fmamk_f32 v82, v82, 0x3e0293ee, v207
	v_fmamk_f32 v83, v83, 0x3e0293ee, v207
	v_fmamk_f32 v84, v84, 0x3e0293ee, v207
	v_fmamk_f32 v85, v85, 0x3e0293ee, v207
	v_fmamk_f32 v86, v86, 0x3e0293ee, v207
	v_fmamk_f32 v87, v87, 0x3e0293ee, v207
	v_fmamk_f32 v88, v88, 0x3e0293ee, v207
	v_fmamk_f32 v89, v89, 0x3e0293ee, v207
	v_fmamk_f32 v90, v90, 0x3e0293ee, v207
	v_fmamk_f32 v91, v91, 0x3e0293ee, v207
	v_fmamk_f32 v92, v92, 0x3e0293ee, v207
	v_fmamk_f32 v93, v93, 0x3e0293ee, v207
	v_fmamk_f32 v94, v94, 0x3e0293ee, v207
	v_fmamk_f32 v95, v95, 0x3e0293ee, v207
	v_exp_f32_e32 v160, v80
	v_exp_f32_e32 v175, v81
	v_exp_f32_e32 v161, v82
	v_exp_f32_e32 v174, v83
	v_exp_f32_e32 v162, v84
	v_exp_f32_e32 v173, v85
	v_exp_f32_e32 v163, v86
	v_exp_f32_e32 v172, v87
	v_exp_f32_e32 v164, v88
	v_exp_f32_e32 v171, v89
	v_exp_f32_e32 v165, v90
	v_exp_f32_e32 v170, v91
	v_exp_f32_e32 v166, v92
	v_exp_f32_e32 v169, v93
	v_exp_f32_e32 v167, v94
	v_exp_f32_e32 v168, v95
	v_fmamk_f32 v216, v64, 0x3e0293ee, v207
	v_fmamk_f32 v217, v65, 0x3e0293ee, v207
	v_fmamk_f32 v218, v66, 0x3e0293ee, v207
	v_fmamk_f32 v219, v67, 0x3e0293ee, v207
	v_fmamk_f32 v224, v68, 0x3e0293ee, v207
	v_fmamk_f32 v209, v69, 0x3e0293ee, v207
	v_fmamk_f32 v210, v70, 0x3e0293ee, v207
	v_fmamk_f32 v211, v71, 0x3e0293ee, v207
	v_fmamk_f32 v212, v72, 0x3e0293ee, v207
	v_fmamk_f32 v213, v73, 0x3e0293ee, v207
	v_fmamk_f32 v214, v74, 0x3e0293ee, v207
	v_fmamk_f32 v215, v75, 0x3e0293ee, v207
	v_fmamk_f32 v208, v76, 0x3e0293ee, v207
	v_fmamk_f32 v225, v77, 0x3e0293ee, v207
	v_fmamk_f32 v226, v78, 0x3e0293ee, v207
	v_fmac_f32_e32 v207, 0x3e0293ee, v79
	s_waitcnt lgkmcnt(0)
	s_barrier
	ds_read_b128 v[64:67], v189 offset:32768
	ds_read_b128 v[68:71], v189 offset:40960
	ds_read_b128 v[228:231], v199 offset:32768
	ds_read_b128 v[232:235], v199 offset:40960
	ds_read_b128 v[240:243], v192 offset:32768
	ds_read_b128 v[244:247], v192 offset:40960
	v_exp_f32_e32 v221, v207
	v_add_f32_e32 v207, 0, v160
	s_waitcnt lgkmcnt(5)
	v_mfma_f32_32x32x16_bf16 v[80:95], v[64:67], v[112:115], 0
	v_add_f32_e32 v207, v175, v207
	v_add_f32_e32 v207, v161, v207
	v_add_f32_e32 v207, v174, v207
	v_add_f32_e32 v207, v162, v207
	v_add_f32_e32 v207, v173, v207
	v_add_f32_e32 v207, v163, v207
	v_add_f32_e32 v207, v172, v207
	s_waitcnt lgkmcnt(4)
	v_mfma_f32_32x32x16_bf16 v[64:79], v[68:71], v[112:115], 0
	v_add_f32_e32 v207, v164, v207
	v_add_f32_e32 v207, v171, v207
	v_add_f32_e32 v207, v165, v207
	v_add_f32_e32 v207, v170, v207
	v_exp_f32_e32 v194, v216
	v_add_f32_e32 v207, v166, v207
	v_exp_f32_e32 v195, v217
	s_waitcnt lgkmcnt(3)
	v_mfma_f32_32x32x16_bf16 v[80:95], v[228:231], v[108:111], v[80:95]
	v_add_f32_e32 v207, v169, v207
	v_exp_f32_e32 v196, v218
	v_add_f32_e32 v207, v167, v207
	v_exp_f32_e32 v197, v219
	v_add_f32_e32 v207, v168, v207
	v_exp_f32_e32 v216, v224
	v_add_f32_e32 v207, v194, v207
	s_waitcnt lgkmcnt(2)
	v_mfma_f32_32x32x16_bf16 v[64:79], v[232:235], v[108:111], v[64:79]
	ds_read_b128 v[228:231], v191 offset:32768
	ds_read_b128 v[232:235], v191 offset:40960
	v_exp_f32_e32 v209, v209
	v_add_f32_e32 v207, v195, v207
	v_exp_f32_e32 v210, v210
	v_add_f32_e32 v207, v196, v207
	v_exp_f32_e32 v211, v211
	v_add_f32_e32 v207, v197, v207
	s_waitcnt lgkmcnt(3)
	v_mfma_f32_32x32x16_bf16 v[80:95], v[240:243], v[120:123], v[80:95]
	v_exp_f32_e32 v212, v212
	v_add_f32_e32 v207, v216, v207
	v_exp_f32_e32 v213, v213
	v_add_f32_e32 v207, v209, v207
	v_exp_f32_e32 v214, v214
	v_add_f32_e32 v207, v210, v207
	v_exp_f32_e32 v215, v215
	s_waitcnt lgkmcnt(2)
	v_mfma_f32_32x32x16_bf16 v[64:79], v[244:247], v[120:123], v[64:79]
	ds_read_b128 v[240:243], v189 offset:32896
	ds_read_b128 v[244:247], v189 offset:41088
	v_add_f32_e32 v207, v211, v207
	v_exp_f32_e32 v217, v208
	v_add_f32_e32 v207, v212, v207
	v_exp_f32_e32 v218, v225
	v_add_f32_e32 v207, v213, v207
	v_exp_f32_e32 v219, v226
	s_waitcnt lgkmcnt(3)
	v_mfma_f32_32x32x16_bf16 v[80:95], v[228:231], v[124:127], v[80:95]
	v_add_f32_e32 v207, v214, v207
	v_add_f32_e32 v207, v215, v207
	v_add_f32_e32 v207, v217, v207
	v_add_f32_e32 v207, v218, v207
	v_add_f32_e32 v207, v219, v207
	v_add_f32_e32 v207, v221, v207
	v_mov_b32_e32 v208, v207
	s_waitcnt lgkmcnt(2)
	v_mfma_f32_32x32x16_bf16 v[64:79], v[232:235], v[124:127], v[64:79]
	ds_read_b128 v[228:231], v199 offset:32896
	ds_read_b128 v[232:235], v199 offset:41088
	v_permlane32_swap_b32_e32 v207, v208
	s_waitcnt lgkmcnt(3)
	v_mfma_f32_32x32x16_bf16 v[80:95], v[240:243], v[116:119], v[80:95]
	s_waitcnt lgkmcnt(2)
	v_mfma_f32_32x32x16_bf16 v[64:79], v[244:247], v[116:119], v[64:79]
	ds_read_b128 v[240:243], v192 offset:32896
	ds_read_b128 v[244:247], v192 offset:41088
	s_waitcnt lgkmcnt(3)
	v_mfma_f32_32x32x16_bf16 v[80:95], v[228:231], v[104:107], v[80:95]
	s_waitcnt lgkmcnt(2)
	v_mfma_f32_32x32x16_bf16 v[64:79], v[232:235], v[104:107], v[64:79]
	ds_read_b128 v[228:231], v191 offset:32896
	ds_read_b128 v[232:235], v191 offset:41088
	s_waitcnt lgkmcnt(3)
	v_mfma_f32_32x32x16_bf16 v[80:95], v[240:243], v[100:103], v[80:95]
	s_waitcnt lgkmcnt(2)
	v_mfma_f32_32x32x16_bf16 v[64:79], v[244:247], v[100:103], v[64:79]
	v_cvt_pk_bf16_f32 v160, v160, v175
	v_cvt_pk_bf16_f32 v161, v161, v174
	v_cvt_pk_bf16_f32 v162, v162, v173
	v_cvt_pk_bf16_f32 v163, v163, v172
	v_cvt_pk_bf16_f32 v164, v164, v171
	v_cvt_pk_bf16_f32 v165, v165, v170
	s_waitcnt lgkmcnt(1)
	v_mfma_f32_32x32x16_bf16 v[80:95], v[228:231], v[96:99], v[80:95]
	v_cvt_pk_bf16_f32 v166, v166, v169
	v_cvt_pk_bf16_f32 v167, v167, v168
	v_cvt_pk_bf16_f32 v168, v194, v195
	v_cvt_pk_bf16_f32 v169, v196, v197
	v_cvt_pk_bf16_f32 v170, v216, v209
	v_cvt_pk_bf16_f32 v171, v210, v211
	v_cvt_pk_bf16_f32 v172, v212, v213
	s_waitcnt lgkmcnt(0)
	v_mfma_f32_32x32x16_bf16 v[64:79], v[232:235], v[96:99], v[64:79]
	v_cvt_pk_bf16_f32 v173, v214, v215
	v_cvt_pk_bf16_f32 v174, v217, v218
	v_cvt_pk_bf16_f32 v175, v219, v221
	s_add_i32 s50, s50, 2
	s_cmp_ge_u32 s50, s49
	s_cselect_b64 s[44:45], -1, 0
	s_and_b64 vcc, exec, s[44:45]
	s_cbranch_vccnz .LBB0_581
	global_load_dwordx4 v[128:131], v176, s[52:53]
	global_load_dwordx4 v[132:135], v176, s[52:53] offset:-512
	s_add_u32 s52, s52, 0x18000
	s_addc_u32 s53, s53, 0
	global_load_dwordx4 v[136:139], v176, s[52:53]
	global_load_dwordx4 v[140:143], v176, s[52:53] offset:-512
	s_add_u32 s52, s52, 0x18000
	s_addc_u32 s53, s53, 0
; #define SWAIT() do { if constexpr (SDEPTH == 2) asm volatile("s_waitcnt vmcnt(4)" ::: "memory"); else asm volatile("s_waitcnt vmcnt(0)" ::: "memory"); } while (0)
; #define RESC(a) do { if (__any((a) < 1.f)) { if (hi == 0) al_l[r32] = (a); asm volatile("s_waitcnt lgkmcnt(0)" ::: "memory"); \
;     for (int d = 0; d < 4; ++d) for (int r = 0; r < 16; ++r) o[d][r] *= al_l[crow(r, hi)]; } } while (0)
; __device__ __forceinline__ void partialSM(f32x16& p0, f32x16& p1, float& m_reg, float& mn, float& alpha) {
;     ...
;   float pmax = p0[0]; for (int r = 1; r < 16; ++r) pmax = fmaxf(pmax, p0[r]); for (int r = 0; r < 16; ++r) pmax = fmaxf(pmax, p1[r]);
;   { auto rr = __builtin_amdgcn_permlane32_swap(__float_as_uint(pmax), __float_as_uint(pmax), false, false);
;     pmax = fmaxf(__uint_as_float(rr[0]), __uint_as_float(rr[1])); }
;   if (__builtin_expect(__all(pmax - m_reg <= THR / SCALE), 1)) { mn = m_reg; alpha = 1.f; }
;   else { mn = fmaxf(m_reg, pmax); alpha = __builtin_amdgcn_exp2f((m_reg - mn) * C); m_reg = mn; }
; template <typename TQ>
; __device__ __forceinline__ void attn_dense_body(const TQ* __restrict__ Qb, const bf16* __restrict__ Kh, const bf16* __restrict__ Vh,
;                                                 unsigned short* __restrict__ Ob, int seq, char* lds, const int wave_s) {
;     ...
;     pv_d0(o, vb0 + (int)SHM_V, pa0, pa1, pa2, pa3); partialSM(pA0, pA1, m_reg, mnA, alA);
;     __syncthreads(); SWAIT(); SWRITE(1, SO);
;     RESC(alA); __syncthreads();
.LBB0_581:
	ds_read_b64_tr_b16 v[210:211], v184 offset:16384
	ds_read_b64_tr_b16 v[212:213], v184 offset:18432
	ds_read_b64_tr_b16 v[214:215], v184 offset:20480
	ds_read_b64_tr_b16 v[216:217], v184 offset:22528
	ds_read_b64_tr_b16 v[224:225], v184 offset:24576
	ds_read_b64_tr_b16 v[226:227], v184 offset:26624
	ds_read_b64_tr_b16 v[228:229], v184 offset:28672
	ds_read_b64_tr_b16 v[230:231], v184 offset:30720
	s_waitcnt lgkmcnt(0)
	s_nop 0
	v_mfma_f32_32x32x16_bf16 v[0:15], v[160:163], v[210:213], v[0:15]
	ds_read_b64_tr_b16 v[210:211], v184 offset:16896
	ds_read_b64_tr_b16 v[212:213], v184 offset:18944
	v_mfma_f32_32x32x16_bf16 v[0:15], v[164:167], v[214:217], v[0:15]
	ds_read_b64_tr_b16 v[214:215], v184 offset:20992
	ds_read_b64_tr_b16 v[216:217], v184 offset:23040
	v_mfma_f32_32x32x16_bf16 v[0:15], v[168:171], v[224:227], v[0:15]
	ds_read_b64_tr_b16 v[224:225], v184 offset:25088
	ds_read_b64_tr_b16 v[226:227], v184 offset:27136
	v_mfma_f32_32x32x16_bf16 v[0:15], v[172:175], v[228:231], v[0:15]
	ds_read_b64_tr_b16 v[228:229], v184 offset:29184
	ds_read_b64_tr_b16 v[230:231], v184 offset:31232
	s_waitcnt lgkmcnt(0)
	v_mfma_f32_32x32x16_bf16 v[48:63], v[160:163], v[210:213], v[48:63]
	ds_read_b64_tr_b16 v[210:211], v184 offset:17408
	ds_read_b64_tr_b16 v[212:213], v184 offset:19456
	v_mfma_f32_32x32x16_bf16 v[48:63], v[164:167], v[214:217], v[48:63]
	ds_read_b64_tr_b16 v[214:215], v184 offset:21504
	ds_read_b64_tr_b16 v[216:217], v184 offset:23552
	v_mfma_f32_32x32x16_bf16 v[48:63], v[168:171], v[224:227], v[48:63]
	ds_read_b64_tr_b16 v[224:225], v184 offset:25600
	ds_read_b64_tr_b16 v[226:227], v184 offset:27648
	v_mfma_f32_32x32x16_bf16 v[48:63], v[172:175], v[228:231], v[48:63]
	ds_read_b64_tr_b16 v[228:229], v184 offset:29696
	ds_read_b64_tr_b16 v[230:231], v184 offset:31744
	s_waitcnt lgkmcnt(0)
	v_mfma_f32_32x32x16_bf16 v[32:47], v[160:163], v[210:213], v[32:47]
	ds_read_b64_tr_b16 v[210:211], v184 offset:17920
	ds_read_b64_tr_b16 v[212:213], v184 offset:19968
	v_mfma_f32_32x32x16_bf16 v[32:47], v[164:167], v[214:217], v[32:47]
	ds_read_b64_tr_b16 v[214:215], v184 offset:22016
	ds_read_b64_tr_b16 v[216:217], v184 offset:24064
	v_mfma_f32_32x32x16_bf16 v[32:47], v[168:171], v[224:227], v[32:47]
	ds_read_b64_tr_b16 v[224:225], v184 offset:26112
	ds_read_b64_tr_b16 v[226:227], v184 offset:28160
	v_mfma_f32_32x32x16_bf16 v[32:47], v[172:175], v[228:231], v[32:47]
	ds_read_b64_tr_b16 v[228:229], v184 offset:30208
	ds_read_b64_tr_b16 v[230:231], v184 offset:32256
	s_waitcnt lgkmcnt(0)
	v_mfma_f32_32x32x16_bf16 v[16:31], v[160:163], v[210:213], v[16:31]
	v_max_f32_e32 v160, v80, v81
	v_max3_f32 v160, v160, v82, v83
	v_max3_f32 v160, v160, v84, v85
	v_max3_f32 v160, v160, v86, v87
	v_max3_f32 v160, v160, v88, v89
	v_max3_f32 v160, v160, v90, v91
	v_max3_f32 v160, v160, v92, v93
	v_mfma_f32_32x32x16_bf16 v[16:31], v[164:167], v[214:217], v[16:31]
	v_max3_f32 v160, v160, v94, v95
	v_max3_f32 v160, v160, v64, v65
	v_max3_f32 v160, v160, v66, v67
	v_max3_f32 v160, v160, v68, v69
	v_max3_f32 v160, v160, v70, v71
	v_max3_f32 v160, v160, v72, v73
	v_max3_f32 v160, v160, v74, v75
	v_max3_f32 v160, v160, v76, v77
	v_mfma_f32_32x32x16_bf16 v[16:31], v[168:171], v[224:227], v[16:31]
	v_max3_f32 v160, v160, v78, v79
	v_mov_b32_e32 v161, v160
	s_nop 1
	v_permlane32_swap_b32_e32 v160, v161
	v_max_f32_e32 v160, v160, v161
	v_sub_f32_e32 v161, v160, v206
	v_cmp_ge_f32_e32 vcc, s9, v161
	v_max_f32_e32 v161, v206, v160
	v_mfma_f32_32x32x16_bf16 v[16:31], v[172:175], v[228:231], v[16:31]
	v_sub_f32_e32 v160, v206, v161
	v_mul_f32_e32 v160, 0x3e0293ee, v160
	v_exp_f32_e32 v160, v160
	s_cmp_eq_u64 vcc, exec
	s_cselect_b64 s[40:41], -1, 0
	s_waitcnt vmcnt(4)
	v_cndmask_b32_e64 v160, v160, 1.0, s[40:41]
	v_cmp_gt_f32_e32 vcc, 1.0, v160
	s_waitcnt vmcnt(3)
	ds_write_b128 v187, v[144:147] offset:16384
	s_waitcnt vmcnt(1)
	ds_write_b128 v187, v[156:159] offset:24576
	ds_write_b128 v185, v[148:151] offset:49152
	s_waitcnt vmcnt(0)
	ds_write_b128 v185, v[152:155] offset:57344
	s_cbranch_vccz .LBB0_585
	s_and_saveexec_b64 s[46:47], s[38:39]
	ds_write_b32 v181, v160 offset:128
	s_or_b64 exec, exec, s[46:47]
	s_waitcnt lgkmcnt(0)
	v_add_u32_e32 v156, s1, v180
	ds_read_b128 v[144:147], v156 offset:224
	ds_read_b128 v[148:151], v156 offset:192
	ds_read_b128 v[152:155], v156 offset:160
	ds_read_b128 v[156:159], v156 offset:128
	s_waitcnt lgkmcnt(3)
	v_pk_mul_f32 v[12:13], v[12:13], v[144:145]
	s_waitcnt lgkmcnt(2)
	v_pk_mul_f32 v[8:9], v[8:9], v[148:149]
	s_waitcnt lgkmcnt(1)
	v_pk_mul_f32 v[4:5], v[4:5], v[152:153]
	v_pk_mul_f32 v[14:15], v[14:15], v[146:147]
	v_pk_mul_f32 v[10:11], v[10:11], v[150:151]
	v_pk_mul_f32 v[6:7], v[6:7], v[154:155]
	s_waitcnt lgkmcnt(0)
	v_pk_mul_f32 v[2:3], v[2:3], v[158:159]
	v_pk_mul_f32 v[0:1], v[0:1], v[156:157]
	v_pk_mul_f32 v[60:61], v[60:61], v[144:145]
	v_pk_mul_f32 v[56:57], v[56:57], v[148:149]
	v_pk_mul_f32 v[52:53], v[52:53], v[152:153]
	v_pk_mul_f32 v[62:63], v[62:63], v[146:147]
	v_pk_mul_f32 v[58:59], v[58:59], v[150:151]
	v_pk_mul_f32 v[54:55], v[54:55], v[154:155]
	v_pk_mul_f32 v[50:51], v[50:51], v[158:159]
	v_pk_mul_f32 v[48:49], v[48:49], v[156:157]
	v_pk_mul_f32 v[44:45], v[44:45], v[144:145]
	v_pk_mul_f32 v[40:41], v[40:41], v[148:149]
	v_pk_mul_f32 v[36:37], v[36:37], v[152:153]
	v_pk_mul_f32 v[46:47], v[46:47], v[146:147]
	v_pk_mul_f32 v[42:43], v[42:43], v[150:151]
	v_pk_mul_f32 v[38:39], v[38:39], v[154:155]
	v_pk_mul_f32 v[34:35], v[34:35], v[158:159]
	v_pk_mul_f32 v[32:33], v[32:33], v[156:157]
	v_pk_mul_f32 v[28:29], v[28:29], v[144:145]
	v_pk_mul_f32 v[24:25], v[24:25], v[148:149]
	v_pk_mul_f32 v[20:21], v[20:21], v[152:153]
	v_pk_mul_f32 v[30:31], v[30:31], v[146:147]
	v_pk_mul_f32 v[26:27], v[26:27], v[150:151]
	v_pk_mul_f32 v[22:23], v[22:23], v[154:155]
	v_pk_mul_f32 v[18:19], v[18:19], v[158:159]
	v_pk_mul_f32 v[16:17], v[16:17], v[156:157]
; #define SBAR() __builtin_amdgcn_sched_barrier(0)
; __device__ __forceinline__ void partialSM(f32x16& p0, f32x16& p1, float& m_reg, float& mn, float& alpha) {
;     ...
;   float mnC = -mn * C;
;   for (int r = 0; r < 16; ++r) p0[r] = fmaf(p0[r], C, mnC); for (int r = 0; r < 16; ++r) p1[r] = fmaf(p1[r], C, mnC);
;   for (int r = 0; r < 16; ++r) p0[r] = __builtin_amdgcn_exp2f(p0[r]);
; }
; __device__ __forceinline__ void finishSM(f32x16& p0, f32x16& p1, float alpha, float& l_reg, bf16x8& pa0, bf16x8& pa1, bf16x8& pa2, bf16x8& pa3) {
;   for (int r = 0; r < 16; ++r) p1[r] = __builtin_amdgcn_exp2f(p1[r]);
;   float ps = 0; for (int r = 0; r < 16; ++r) ps += p0[r]; for (int r = 0; r < 16; ++r) ps += p1[r];
;   { auto rr = __builtin_amdgcn_permlane32_swap(__float_as_uint(ps), __float_as_uint(ps), false, false);
;     ps = __uint_as_float(rr[0]) + __uint_as_float(rr[1]); }
;   l_reg = l_reg * alpha + ps;
; template <typename TQ>
; __device__ __forceinline__ void attn_dense_body(const TQ* __restrict__ Qb, const bf16* __restrict__ Kh, const bf16* __restrict__ Vh,
;                                                 unsigned short* __restrict__ Ob, int seq, char* lds, const int wave_s) {
;     ...
;   SBAR(); qkt(pB0, pB1, (bf16*)((char*)K_lds + SHM_K), qr, r32, hi);
.LBB0_585:
	v_xor_b32_e32 v184, 0x8000, v184
	v_xor_b32_e32 v187, 0x8000, v187
	v_xor_b32_e32 v185, 0x18000, v185
	v_cndmask_b32_e64 v164, v161, v206, s[40:41]
	v_mul_f32_e32 v144, 0xbe0293ee, v164
	v_mov_b32_e32 v145, v144
	v_fmamk_f32 v80, v80, 0x3e0293ee, v144
	v_fmamk_f32 v81, v81, 0x3e0293ee, v144
	v_fmamk_f32 v82, v82, 0x3e0293ee, v144
	v_fmamk_f32 v83, v83, 0x3e0293ee, v144
	v_fmamk_f32 v84, v84, 0x3e0293ee, v144
	v_fmamk_f32 v85, v85, 0x3e0293ee, v144
	v_fmamk_f32 v86, v86, 0x3e0293ee, v144
	v_fmamk_f32 v87, v87, 0x3e0293ee, v144
	v_fmamk_f32 v88, v88, 0x3e0293ee, v144
	v_fmamk_f32 v89, v89, 0x3e0293ee, v144
	v_fmamk_f32 v90, v90, 0x3e0293ee, v144
	v_fmamk_f32 v91, v91, 0x3e0293ee, v144
	v_fmamk_f32 v92, v92, 0x3e0293ee, v144
	v_fmamk_f32 v93, v93, 0x3e0293ee, v144
	v_fmamk_f32 v94, v94, 0x3e0293ee, v144
	v_fmac_f32_e32 v145, 0x3e0293ee, v95
	v_exp_f32_e32 v161, v80
	v_exp_f32_e32 v175, v81
	v_exp_f32_e32 v162, v82
	v_exp_f32_e32 v206, v83
	v_exp_f32_e32 v174, v84
	v_exp_f32_e32 v209, v85
	v_exp_f32_e32 v163, v86
	v_exp_f32_e32 v173, v87
	v_exp_f32_e32 v169, v88
	v_exp_f32_e32 v171, v89
	v_exp_f32_e32 v170, v90
	v_exp_f32_e32 v172, v91
	v_exp_f32_e32 v165, v92
	v_exp_f32_e32 v167, v93
	v_exp_f32_e32 v166, v94
	v_exp_f32_e32 v168, v145
	v_pk_fma_f32 v[158:159], v[64:65], s[30:31], v[144:145] op_sel_hi:[1,0,0]
	v_add_f32_e32 v64, v203, v204
	v_fmac_f32_e32 v64, v202, v182
	v_add_f32_e32 v182, v207, v208
	v_pk_fma_f32 v[156:157], v[66:67], s[30:31], v[144:145] op_sel_hi:[1,0,0]
	v_pk_fma_f32 v[152:153], v[68:69], s[30:31], v[144:145] op_sel_hi:[1,0,0]
	v_pk_fma_f32 v[148:149], v[70:71], s[30:31], v[144:145] op_sel_hi:[1,0,0]
	v_pk_fma_f32 v[146:147], v[72:73], s[30:31], v[144:145] op_sel_hi:[1,0,0]
	v_pk_fma_f32 v[154:155], v[74:75], s[30:31], v[144:145] op_sel_hi:[1,0,0]
	v_pk_fma_f32 v[150:151], v[76:77], s[30:31], v[144:145] op_sel_hi:[1,0,0]
	v_pk_fma_f32 v[144:145], v[78:79], s[30:31], v[144:145] op_sel_hi:[1,0,0]
	v_fmac_f32_e32 v182, v64, v205
	s_and_b64 vcc, exec, s[44:45]
	s_waitcnt lgkmcnt(0)
	s_barrier
	s_cbranch_vccnz .LBB0_587
	v_mov_b32_e32 v202, v160
	s_branch .LBB0_575
.LBB0_587:
	ds_read_b128 v[64:67], v189 offset:49152
	ds_read_b128 v[68:71], v189 offset:57344
	s_waitcnt lgkmcnt(1)
	v_mfma_f32_32x32x16_bf16 v[80:95], v[64:67], v[112:115], 0
	s_waitcnt lgkmcnt(0)
	v_mfma_f32_32x32x16_bf16 v[64:79], v[68:71], v[112:115], 0
	ds_read_b128 v[112:115], v199 offset:49152
	ds_read_b128 v[128:131], v199 offset:57344
	s_waitcnt lgkmcnt(1)
	v_mfma_f32_32x32x16_bf16 v[80:95], v[112:115], v[108:111], v[80:95]
	s_waitcnt lgkmcnt(0)
	v_mfma_f32_32x32x16_bf16 v[64:79], v[128:131], v[108:111], v[64:79]
	ds_read_b128 v[108:111], v192 offset:49152
	ds_read_b128 v[112:115], v192 offset:57344
	s_waitcnt lgkmcnt(1)
	v_mfma_f32_32x32x16_bf16 v[80:95], v[108:111], v[120:123], v[80:95]
	s_waitcnt lgkmcnt(0)
	v_mfma_f32_32x32x16_bf16 v[64:79], v[112:115], v[120:123], v[64:79]
	ds_read_b128 v[108:111], v191 offset:49152
	ds_read_b128 v[112:115], v191 offset:57344
	v_exp_f32_e32 v120, v144
	v_exp_f32_e32 v121, v145
	s_waitcnt lgkmcnt(1)
	v_mfma_f32_32x32x16_bf16 v[80:95], v[108:111], v[124:127], v[80:95]
	s_waitcnt lgkmcnt(0)
	v_mfma_f32_32x32x16_bf16 v[64:79], v[112:115], v[124:127], v[64:79]
	ds_read_b128 v[108:111], v189 offset:49280
	ds_read_b128 v[112:115], v189 offset:57472
	s_waitcnt lgkmcnt(1)
	v_mfma_f32_32x32x16_bf16 v[80:95], v[108:111], v[116:119], v[80:95]
	s_waitcnt lgkmcnt(0)
	v_mfma_f32_32x32x16_bf16 v[64:79], v[112:115], v[116:119], v[64:79]
	ds_read_b128 v[108:111], v199 offset:49280
	ds_read_b128 v[112:115], v199 offset:57472
	v_exp_f32_e32 v116, v154
	v_exp_f32_e32 v117, v155
	v_exp_f32_e32 v118, v150
	v_exp_f32_e32 v119, v151
	s_waitcnt lgkmcnt(1)
	v_mfma_f32_32x32x16_bf16 v[80:95], v[108:111], v[104:107], v[80:95]
	s_waitcnt lgkmcnt(0)
	v_mfma_f32_32x32x16_bf16 v[64:79], v[112:115], v[104:107], v[64:79]
	ds_read_b128 v[104:107], v192 offset:49280
	ds_read_b128 v[108:111], v192 offset:57472
	v_exp_f32_e32 v112, v148
	v_exp_f32_e32 v113, v149
	v_exp_f32_e32 v114, v146
	v_exp_f32_e32 v115, v147
	s_waitcnt lgkmcnt(1)
	v_mfma_f32_32x32x16_bf16 v[80:95], v[104:107], v[100:103], v[80:95]
	s_waitcnt lgkmcnt(0)
	v_mfma_f32_32x32x16_bf16 v[64:79], v[108:111], v[100:103], v[64:79]
	ds_read_b128 v[100:103], v191 offset:49280
	ds_read_b128 v[104:107], v191 offset:57472
	v_exp_f32_e32 v108, v156
	v_exp_f32_e32 v109, v157
	v_exp_f32_e32 v110, v152
	v_exp_f32_e32 v111, v153
	s_waitcnt lgkmcnt(1)
	v_mfma_f32_32x32x16_bf16 v[80:95], v[100:103], v[96:99], v[80:95]
	s_waitcnt lgkmcnt(0)
; #define SBAR() __builtin_amdgcn_sched_barrier(0)
; #define RESC(a) do { if (__any((a) < 1.f)) { if (hi == 0) al_l[r32] = (a); asm volatile("s_waitcnt lgkmcnt(0)" ::: "memory"); \
;     for (int d = 0; d < 4; ++d) for (int r = 0; r < 16; ++r) o[d][r] *= al_l[crow(r, hi)]; } } while (0)
; __device__ __forceinline__ void finishSM(f32x16& p0, f32x16& p1, float alpha, float& l_reg, bf16x8& pa0, bf16x8& pa1, bf16x8& pa2, bf16x8& pa3) {
;   for (int r = 0; r < 16; ++r) p1[r] = __builtin_amdgcn_exp2f(p1[r]);
;   float ps = 0; for (int r = 0; r < 16; ++r) ps += p0[r]; for (int r = 0; r < 16; ++r) ps += p1[r];
;   { auto rr = __builtin_amdgcn_permlane32_swap(__float_as_uint(ps), __float_as_uint(ps), false, false);
;     ps = __uint_as_float(rr[0]) + __uint_as_float(rr[1]); }
;   l_reg = l_reg * alpha + ps;
;     ...
;   PK4(p0, 0, pa0); PK4(p0, 8, pa1); PK4(p1, 0, pa2); PK4(p1, 8, pa3);
; template <typename TQ>
; __device__ __forceinline__ void attn_dense_body(const TQ* __restrict__ Qb, const bf16* __restrict__ Kh, const bf16* __restrict__ Vh,
;                                                 unsigned short* __restrict__ Ob, int seq, char* lds, const int wave_s) {
;     ...
;   finishSM(pA0, pA1, alA, l_reg, pa0, pa1, pa2, pa3); SBAR();
;   pv_d0(o, vb0, pa0, pa1, pa2, pa3); partialSM(pB0, pB1, m_reg, mnB, alB);
;   __syncthreads(); RESC(alB);
	v_mfma_f32_32x32x16_bf16 v[64:79], v[104:107], v[96:99], v[64:79]
	v_add_f32_e32 v96, 0, v161
	v_add_f32_e32 v96, v175, v96
	v_add_f32_e32 v96, v162, v96
	v_add_f32_e32 v96, v206, v96
	v_add_f32_e32 v96, v174, v96
	v_add_f32_e32 v96, v209, v96
	v_add_f32_e32 v96, v163, v96
	v_add_f32_e32 v96, v173, v96
	v_add_f32_e32 v96, v169, v96
	v_add_f32_e32 v96, v171, v96
	v_add_f32_e32 v96, v170, v96
	v_add_f32_e32 v96, v172, v96
	v_exp_f32_e32 v106, v158
	v_add_f32_e32 v96, v165, v96
	v_exp_f32_e32 v107, v159
	v_add_f32_e32 v96, v167, v96
	v_add_f32_e32 v96, v166, v96
	v_add_f32_e32 v96, v168, v96
	v_add_f32_e32 v96, v106, v96
	v_add_f32_e32 v96, v107, v96
	v_add_f32_e32 v96, v108, v96
	v_add_f32_e32 v96, v109, v96
	v_add_f32_e32 v96, v110, v96
	v_add_f32_e32 v96, v111, v96
	v_add_f32_e32 v96, v112, v96
	v_add_f32_e32 v96, v113, v96
	v_add_f32_e32 v96, v114, v96
	v_add_f32_e32 v96, v115, v96
	v_add_f32_e32 v96, v116, v96
	v_add_f32_e32 v96, v117, v96
	v_add_f32_e32 v96, v118, v96
	v_add_f32_e32 v96, v119, v96
	v_add_f32_e32 v96, v120, v96
	v_add_f32_e32 v96, v121, v96
	v_mov_b32_e32 v97, v96
	v_cvt_pk_bf16_f32 v98, v161, v175
	v_cvt_pk_bf16_f32 v99, v162, v206
	v_cvt_pk_bf16_f32 v100, v174, v209
	v_cvt_pk_bf16_f32 v101, v163, v173
	s_nop 1
	v_permlane32_swap_b32_e32 v96, v97
	v_cvt_pk_bf16_f32 v102, v169, v171
	v_cvt_pk_bf16_f32 v103, v170, v172
	v_cvt_pk_bf16_f32 v104, v165, v167
	v_cvt_pk_bf16_f32 v105, v166, v168
	v_cvt_pk_bf16_f32 v106, v106, v107
	v_cvt_pk_bf16_f32 v107, v108, v109
	v_cvt_pk_bf16_f32 v108, v110, v111
	v_cvt_pk_bf16_f32 v109, v112, v113
	v_cvt_pk_bf16_f32 v110, v114, v115
	v_cvt_pk_bf16_f32 v111, v116, v117
	v_cvt_pk_bf16_f32 v112, v118, v119
	v_cvt_pk_bf16_f32 v113, v120, v121
	s_nop 0
	ds_read_b64_tr_b16 v[114:115], v184 offset:0
	ds_read_b64_tr_b16 v[116:117], v184 offset:0x800
	ds_read_b64_tr_b16 v[118:119], v184 offset:0x1000
	ds_read_b64_tr_b16 v[120:121], v184 offset:0x1800
	ds_read_b64_tr_b16 v[122:123], v184 offset:0x2000
	ds_read_b64_tr_b16 v[124:125], v184 offset:0x2800
	ds_read_b64_tr_b16 v[126:127], v184 offset:0x3000
	ds_read_b64_tr_b16 v[128:129], v184 offset:0x3800
	s_waitcnt lgkmcnt(0)
	s_nop 0
	v_mfma_f32_32x32x16_bf16 v[0:15], v[98:101], v[114:117], v[0:15]
	ds_read_b64_tr_b16 v[114:115], v184 offset:0x200
	ds_read_b64_tr_b16 v[116:117], v184 offset:0xa00
	v_mfma_f32_32x32x16_bf16 v[0:15], v[102:105], v[118:121], v[0:15]
	ds_read_b64_tr_b16 v[118:119], v184 offset:0x1200
	ds_read_b64_tr_b16 v[120:121], v184 offset:0x1a00
	v_mfma_f32_32x32x16_bf16 v[0:15], v[106:109], v[122:125], v[0:15]
	ds_read_b64_tr_b16 v[122:123], v184 offset:0x2200
	ds_read_b64_tr_b16 v[124:125], v184 offset:0x2a00
	v_mfma_f32_32x32x16_bf16 v[0:15], v[110:113], v[126:129], v[0:15]
	ds_read_b64_tr_b16 v[126:127], v184 offset:0x3200
	ds_read_b64_tr_b16 v[128:129], v184 offset:0x3a00
	s_waitcnt lgkmcnt(0)
	v_mfma_f32_32x32x16_bf16 v[48:63], v[98:101], v[114:117], v[48:63]
	ds_read_b64_tr_b16 v[114:115], v184 offset:0x400
	ds_read_b64_tr_b16 v[116:117], v184 offset:0xc00
	v_mfma_f32_32x32x16_bf16 v[48:63], v[102:105], v[118:121], v[48:63]
	ds_read_b64_tr_b16 v[118:119], v184 offset:0x1400
	ds_read_b64_tr_b16 v[120:121], v184 offset:0x1c00
	v_mfma_f32_32x32x16_bf16 v[48:63], v[106:109], v[122:125], v[48:63]
	ds_read_b64_tr_b16 v[122:123], v184 offset:0x2400
	ds_read_b64_tr_b16 v[124:125], v184 offset:0x2c00
	v_mfma_f32_32x32x16_bf16 v[48:63], v[110:113], v[126:129], v[48:63]
	ds_read_b64_tr_b16 v[126:127], v184 offset:0x3400
	ds_read_b64_tr_b16 v[128:129], v184 offset:0x3c00
	s_waitcnt lgkmcnt(0)
	v_mfma_f32_32x32x16_bf16 v[32:47], v[98:101], v[114:117], v[32:47]
	ds_read_b64_tr_b16 v[114:115], v184 offset:0x600
	ds_read_b64_tr_b16 v[116:117], v184 offset:0xe00
	v_mfma_f32_32x32x16_bf16 v[32:47], v[102:105], v[118:121], v[32:47]
	ds_read_b64_tr_b16 v[118:119], v184 offset:0x1600
	ds_read_b64_tr_b16 v[120:121], v184 offset:0x1e00
	v_mfma_f32_32x32x16_bf16 v[32:47], v[106:109], v[122:125], v[32:47]
	ds_read_b64_tr_b16 v[122:123], v184 offset:0x2600
	ds_read_b64_tr_b16 v[124:125], v184 offset:0x2e00
	v_mfma_f32_32x32x16_bf16 v[32:47], v[110:113], v[126:129], v[32:47]
	ds_read_b64_tr_b16 v[126:127], v184 offset:0x3600
	ds_read_b64_tr_b16 v[128:129], v184 offset:0x3e00
	s_waitcnt lgkmcnt(0)
	v_mfma_f32_32x32x16_bf16 v[16:31], v[98:101], v[114:117], v[16:31]
	v_max_f32_e32 v98, v81, v81
	v_max_f32_e32 v99, v80, v80
	v_max_f32_e32 v98, v99, v98
	v_max3_f32 v98, v98, v82, v83
	v_max3_f32 v98, v98, v84, v85
	v_max3_f32 v98, v98, v86, v87
	v_max3_f32 v98, v98, v88, v89
	v_max3_f32 v98, v98, v90, v91
	v_max3_f32 v98, v98, v92, v93
	v_mfma_f32_32x32x16_bf16 v[16:31], v[102:105], v[118:121], v[16:31]
	v_max3_f32 v98, v98, v94, v95
	v_max3_f32 v98, v98, v64, v65
	v_max3_f32 v98, v98, v66, v67
	v_max3_f32 v98, v98, v68, v69
	v_max3_f32 v98, v98, v70, v71
	v_max3_f32 v98, v98, v72, v73
	v_max3_f32 v98, v98, v74, v75
	v_max3_f32 v98, v98, v76, v77
	v_mfma_f32_32x32x16_bf16 v[16:31], v[106:109], v[122:125], v[16:31]
	v_max3_f32 v98, v98, v78, v79
	v_mov_b32_e32 v99, v98
	s_nop 1
	v_permlane32_swap_b32_e32 v98, v99
	v_max_f32_e32 v99, v99, v99
	v_max_f32_e32 v98, v98, v98
	v_max_f32_e32 v98, v98, v99
	v_sub_f32_e32 v99, v98, v164
	v_cmp_ge_f32_e32 vcc, s9, v99
	v_max_f32_e32 v99, v164, v164
	v_max_f32_e32 v99, v99, v98
	v_mfma_f32_32x32x16_bf16 v[16:31], v[110:113], v[126:129], v[16:31]
	v_sub_f32_e32 v98, v164, v99
	v_mul_f32_e32 v98, 0x3e0293ee, v98
	v_exp_f32_e32 v98, v98
	s_cmp_eq_u64 vcc, exec
	s_cselect_b64 s[40:41], -1, 0
	v_cndmask_b32_e64 v98, v98, 1.0, s[40:41]
	v_cmp_gt_f32_e32 vcc, 1.0, v98
	s_barrier
	s_cbranch_vccz .LBB0_591
	s_and_saveexec_b64 s[44:45], s[38:39]
	ds_write_b32 v181, v98 offset:128
	s_or_b64 exec, exec, s[44:45]
	s_waitcnt lgkmcnt(0)
	v_add_u32_e32 v112, s1, v180
	ds_read_b128 v[100:103], v112 offset:224
	ds_read_b128 v[104:107], v112 offset:192
	ds_read_b128 v[108:111], v112 offset:160
	ds_read_b128 v[112:115], v112 offset:128
	s_waitcnt lgkmcnt(3)
	v_pk_mul_f32 v[12:13], v[12:13], v[100:101]
	s_waitcnt lgkmcnt(2)
	v_pk_mul_f32 v[8:9], v[8:9], v[104:105]
	s_waitcnt lgkmcnt(1)
	v_pk_mul_f32 v[4:5], v[4:5], v[108:109]
	v_pk_mul_f32 v[14:15], v[14:15], v[102:103]
	v_pk_mul_f32 v[10:11], v[10:11], v[106:107]
	v_pk_mul_f32 v[6:7], v[6:7], v[110:111]
	s_waitcnt lgkmcnt(0)
	v_pk_mul_f32 v[2:3], v[2:3], v[114:115]
	v_pk_mul_f32 v[0:1], v[0:1], v[112:113]
	v_pk_mul_f32 v[60:61], v[60:61], v[100:101]
	v_pk_mul_f32 v[56:57], v[56:57], v[104:105]
	v_pk_mul_f32 v[52:53], v[52:53], v[108:109]
	v_pk_mul_f32 v[62:63], v[62:63], v[102:103]
	v_pk_mul_f32 v[58:59], v[58:59], v[106:107]
	v_pk_mul_f32 v[54:55], v[54:55], v[110:111]
	v_pk_mul_f32 v[50:51], v[50:51], v[114:115]
	v_pk_mul_f32 v[48:49], v[48:49], v[112:113]
	v_pk_mul_f32 v[44:45], v[44:45], v[100:101]
	v_pk_mul_f32 v[40:41], v[40:41], v[104:105]
	v_pk_mul_f32 v[36:37], v[36:37], v[108:109]
	v_pk_mul_f32 v[46:47], v[46:47], v[102:103]
	v_pk_mul_f32 v[42:43], v[42:43], v[106:107]
	v_pk_mul_f32 v[38:39], v[38:39], v[110:111]
	v_pk_mul_f32 v[34:35], v[34:35], v[114:115]
	v_pk_mul_f32 v[32:33], v[32:33], v[112:113]
	v_pk_mul_f32 v[28:29], v[28:29], v[100:101]
	v_pk_mul_f32 v[24:25], v[24:25], v[104:105]
	v_pk_mul_f32 v[20:21], v[20:21], v[108:109]
	v_pk_mul_f32 v[30:31], v[30:31], v[102:103]
	v_pk_mul_f32 v[26:27], v[26:27], v[106:107]
	v_pk_mul_f32 v[22:23], v[22:23], v[110:111]
	v_pk_mul_f32 v[18:19], v[18:19], v[114:115]
	v_pk_mul_f32 v[16:17], v[16:17], v[112:113]
; #define SBAR() __builtin_amdgcn_sched_barrier(0)
; __device__ __forceinline__ void partialSM(f32x16& p0, f32x16& p1, float& m_reg, float& mn, float& alpha) {
;     ...
;   float mnC = -mn * C;
;   for (int r = 0; r < 16; ++r) p0[r] = fmaf(p0[r], C, mnC); for (int r = 0; r < 16; ++r) p1[r] = fmaf(p1[r], C, mnC);
;   for (int r = 0; r < 16; ++r) p0[r] = __builtin_amdgcn_exp2f(p0[r]);
; }
; __device__ __forceinline__ void finishSM(f32x16& p0, f32x16& p1, float alpha, float& l_reg, bf16x8& pa0, bf16x8& pa1, bf16x8& pa2, bf16x8& pa3) {
;   for (int r = 0; r < 16; ++r) p1[r] = __builtin_amdgcn_exp2f(p1[r]);
;   float ps = 0; for (int r = 0; r < 16; ++r) ps += p0[r]; for (int r = 0; r < 16; ++r) ps += p1[r];
;   { auto rr = __builtin_amdgcn_permlane32_swap(__float_as_uint(ps), __float_as_uint(ps), false, false);
;     ps = __uint_as_float(rr[0]) + __uint_as_float(rr[1]); }
;   l_reg = l_reg * alpha + ps;
;     ...
;   PK4(p0, 0, pa0); PK4(p0, 8, pa1); PK4(p1, 0, pa2); PK4(p1, 8, pa3);
; template <typename TQ>
; __device__ __forceinline__ void attn_dense_body(const TQ* __restrict__ Qb, const bf16* __restrict__ Kh, const bf16* __restrict__ Vh,
;                                                 unsigned short* __restrict__ Ob, int seq, char* lds, const int wave_s) {
;     ...
;   finishSM(pB0, pB1, alB, l_reg, pa0, pa1, pa2, pa3); SBAR();
;   pv_d0(o, vb0 + (int)SHM_V, pa0, pa1, pa2, pa3);
;   if (hi == 0) li_l[r32] = l_reg; asm volatile("s_waitcnt lgkmcnt(0)" ::: "memory");
.LBB0_591:
	v_cndmask_b32_e64 v99, v99, v164, s[40:41]
	v_mul_f32_e32 v99, 0xbe0293ee, v99
	v_fmamk_f32 v80, v80, 0x3e0293ee, v99
	v_fmamk_f32 v81, v81, 0x3e0293ee, v99
	v_fmamk_f32 v100, v82, 0x3e0293ee, v99
	v_exp_f32_e32 v82, v80
	v_fmamk_f32 v101, v84, 0x3e0293ee, v99
	v_exp_f32_e32 v84, v81
	v_fmamk_f32 v83, v83, 0x3e0293ee, v99
	v_exp_f32_e32 v80, v100
	v_fmamk_f32 v64, v64, 0x3e0293ee, v99
	v_exp_f32_e32 v83, v83
	v_fmamk_f32 v102, v85, 0x3e0293ee, v99
	v_fmamk_f32 v111, v94, 0x3e0293ee, v99
	v_fmamk_f32 v94, v75, 0x3e0293ee, v99
	v_exp_f32_e32 v75, v101
	v_exp_f32_e32 v100, v64
	v_add_f32_e32 v64, 0, v82
	v_fmamk_f32 v103, v86, 0x3e0293ee, v99
	v_exp_f32_e32 v81, v102
	v_add_f32_e32 v64, v84, v64
	v_fmamk_f32 v104, v87, 0x3e0293ee, v99
	v_fmamk_f32 v110, v93, 0x3e0293ee, v99
	v_fmamk_f32 v93, v74, 0x3e0293ee, v99
	v_exp_f32_e32 v74, v103
	v_add_f32_e32 v64, v80, v64
	v_fmamk_f32 v105, v88, 0x3e0293ee, v99
	v_fmamk_f32 v112, v95, 0x3e0293ee, v99
	v_fmamk_f32 v95, v76, 0x3e0293ee, v99
	v_exp_f32_e32 v76, v104
	v_add_f32_e32 v64, v83, v64
	v_fmamk_f32 v106, v89, 0x3e0293ee, v99
	v_fmamk_f32 v107, v90, 0x3e0293ee, v99
	v_fmamk_f32 v90, v71, 0x3e0293ee, v99
	v_exp_f32_e32 v71, v105
	v_add_f32_e32 v64, v75, v64
	v_fmamk_f32 v109, v92, 0x3e0293ee, v99
	v_fmamk_f32 v92, v73, 0x3e0293ee, v99
	v_exp_f32_e32 v73, v106
	v_add_f32_e32 v64, v81, v64
	v_fmamk_f32 v108, v91, 0x3e0293ee, v99
	v_fmamk_f32 v88, v69, 0x3e0293ee, v99
	v_exp_f32_e32 v69, v107
	v_add_f32_e32 v64, v74, v64
	v_fmamk_f32 v91, v72, 0x3e0293ee, v99
	v_exp_f32_e32 v72, v108
	v_add_f32_e32 v64, v76, v64
	v_fmamk_f32 v86, v67, 0x3e0293ee, v99
	v_exp_f32_e32 v67, v109
	v_add_f32_e32 v64, v71, v64
	v_fmamk_f32 v89, v70, 0x3e0293ee, v99
	v_exp_f32_e32 v70, v110
	v_add_f32_e32 v64, v73, v64
	v_fmamk_f32 v85, v66, 0x3e0293ee, v99
	v_exp_f32_e32 v66, v111
	v_add_f32_e32 v64, v69, v64
	v_fmamk_f32 v87, v68, 0x3e0293ee, v99
	v_exp_f32_e32 v68, v112
	v_add_f32_e32 v64, v72, v64
	v_fmamk_f32 v65, v65, 0x3e0293ee, v99
	v_add_f32_e32 v64, v67, v64
	v_exp_f32_e32 v101, v65
	v_add_f32_e32 v64, v70, v64
	v_exp_f32_e32 v85, v85
	v_add_f32_e32 v64, v66, v64
	v_exp_f32_e32 v86, v86
	v_add_f32_e32 v64, v68, v64
	v_exp_f32_e32 v87, v87
	v_add_f32_e32 v64, v100, v64
	v_exp_f32_e32 v88, v88
	v_add_f32_e32 v64, v101, v64
	v_exp_f32_e32 v89, v89
	v_add_f32_e32 v64, v85, v64
	v_exp_f32_e32 v90, v90
	v_add_f32_e32 v64, v86, v64
	v_exp_f32_e32 v91, v91
	v_add_f32_e32 v64, v87, v64
	v_exp_f32_e32 v92, v92
	v_add_f32_e32 v64, v88, v64
	v_exp_f32_e32 v93, v93
	v_add_f32_e32 v64, v89, v64
	v_exp_f32_e32 v94, v94
	v_add_f32_e32 v64, v90, v64
	v_fmamk_f32 v77, v77, 0x3e0293ee, v99
	v_exp_f32_e32 v95, v95
	v_add_f32_e32 v64, v91, v64
	v_fmamk_f32 v78, v78, 0x3e0293ee, v99
	v_exp_f32_e32 v102, v77
	v_add_f32_e32 v64, v92, v64
	v_fmac_f32_e32 v99, 0x3e0293ee, v79
	v_exp_f32_e32 v103, v78
	v_add_f32_e32 v64, v93, v64
	v_exp_f32_e32 v99, v99
	v_add_f32_e32 v64, v94, v64
	v_add_f32_e32 v64, v95, v64
	v_add_f32_e32 v64, v102, v64
	v_add_f32_e32 v64, v103, v64
	v_add_f32_e32 v64, v99, v64
	v_mov_b32_e32 v65, v64
	s_nop 1
	v_permlane32_swap_b32_e32 v64, v65
	v_cvt_pk_bf16_f32 v78, v82, v84
	v_cvt_pk_bf16_f32 v79, v80, v83
	v_cvt_pk_bf16_f32 v80, v75, v81
	v_cvt_pk_bf16_f32 v81, v74, v76
	v_cvt_pk_bf16_f32 v74, v71, v73
	v_cvt_pk_bf16_f32 v75, v69, v72
	v_cvt_pk_bf16_f32 v76, v67, v70
	v_cvt_pk_bf16_f32 v77, v66, v68
	v_cvt_pk_bf16_f32 v66, v100, v101
	v_cvt_pk_bf16_f32 v67, v85, v86
	v_cvt_pk_bf16_f32 v68, v87, v88
	v_cvt_pk_bf16_f32 v69, v89, v90
	v_cvt_pk_bf16_f32 v70, v91, v92
	v_cvt_pk_bf16_f32 v71, v93, v94
	v_cvt_pk_bf16_f32 v72, v95, v102
	v_cvt_pk_bf16_f32 v73, v103, v99
	s_nop 0
	ds_read_b64_tr_b16 v[82:83], v184 offset:16384
	ds_read_b64_tr_b16 v[84:85], v184 offset:18432
	ds_read_b64_tr_b16 v[86:87], v184 offset:20480
	ds_read_b64_tr_b16 v[88:89], v184 offset:22528
	ds_read_b64_tr_b16 v[90:91], v184 offset:24576
	ds_read_b64_tr_b16 v[92:93], v184 offset:26624
	ds_read_b64_tr_b16 v[100:101], v184 offset:28672
	ds_read_b64_tr_b16 v[102:103], v184 offset:30720
	s_waitcnt lgkmcnt(0)
	s_nop 0
	v_mfma_f32_32x32x16_bf16 v[0:15], v[78:81], v[82:85], v[0:15]
	ds_read_b64_tr_b16 v[82:83], v184 offset:16896
	ds_read_b64_tr_b16 v[84:85], v184 offset:18944
	v_mfma_f32_32x32x16_bf16 v[0:15], v[74:77], v[86:89], v[0:15]
	ds_read_b64_tr_b16 v[86:87], v184 offset:20992
	ds_read_b64_tr_b16 v[88:89], v184 offset:23040
	v_mfma_f32_32x32x16_bf16 v[0:15], v[66:69], v[90:93], v[0:15]
	ds_read_b64_tr_b16 v[90:91], v184 offset:25088
	ds_read_b64_tr_b16 v[92:93], v184 offset:27136
	v_mfma_f32_32x32x16_bf16 v[0:15], v[70:73], v[100:103], v[0:15]
	ds_read_b64_tr_b16 v[100:101], v184 offset:29184
	ds_read_b64_tr_b16 v[102:103], v184 offset:31232
	s_waitcnt lgkmcnt(0)
	v_mfma_f32_32x32x16_bf16 v[48:63], v[78:81], v[82:85], v[48:63]
	ds_read_b64_tr_b16 v[82:83], v184 offset:17408
	ds_read_b64_tr_b16 v[84:85], v184 offset:19456
	v_mfma_f32_32x32x16_bf16 v[48:63], v[74:77], v[86:89], v[48:63]
	ds_read_b64_tr_b16 v[86:87], v184 offset:21504
	ds_read_b64_tr_b16 v[88:89], v184 offset:23552
	v_mfma_f32_32x32x16_bf16 v[48:63], v[66:69], v[90:93], v[48:63]
	ds_read_b64_tr_b16 v[90:91], v184 offset:25600
	ds_read_b64_tr_b16 v[92:93], v184 offset:27648
	v_mfma_f32_32x32x16_bf16 v[48:63], v[70:73], v[100:103], v[48:63]
	ds_read_b64_tr_b16 v[100:101], v184 offset:29696
	ds_read_b64_tr_b16 v[102:103], v184 offset:31744
	s_waitcnt lgkmcnt(0)
	v_mfma_f32_32x32x16_bf16 v[32:47], v[78:81], v[82:85], v[32:47]
	ds_read_b64_tr_b16 v[82:83], v184 offset:17920
	ds_read_b64_tr_b16 v[84:85], v184 offset:19968
	v_mfma_f32_32x32x16_bf16 v[32:47], v[74:77], v[86:89], v[32:47]
	ds_read_b64_tr_b16 v[86:87], v184 offset:22016
	ds_read_b64_tr_b16 v[88:89], v184 offset:24064
	v_mfma_f32_32x32x16_bf16 v[32:47], v[66:69], v[90:93], v[32:47]
	ds_read_b64_tr_b16 v[90:91], v184 offset:26112
	ds_read_b64_tr_b16 v[92:93], v184 offset:28160
	v_mfma_f32_32x32x16_bf16 v[32:47], v[70:73], v[100:103], v[32:47]
	ds_read_b64_tr_b16 v[100:101], v184 offset:30208
	ds_read_b64_tr_b16 v[102:103], v184 offset:32256
	s_waitcnt lgkmcnt(0)
	v_mfma_f32_32x32x16_bf16 v[16:31], v[78:81], v[82:85], v[16:31]
	v_mfma_f32_32x32x16_bf16 v[16:31], v[74:77], v[86:89], v[16:31]
	v_mfma_f32_32x32x16_bf16 v[16:31], v[66:69], v[90:93], v[16:31]
	v_mfma_f32_32x32x16_bf16 v[16:31], v[70:73], v[100:103], v[16:31]
	s_and_saveexec_b64 s[40:41], s[38:39]
	s_cbranch_execz .LBB0_569
	v_add_f32_e32 v66, v96, v97
	v_fmac_f32_e32 v66, v182, v160
	v_add_f32_e32 v64, v64, v65
	v_fmac_f32_e32 v64, v66, v98
	ds_write_b32 v181, v64
	s_branch .LBB0_569
